# k12
# speedup vs baseline: 1.1154x; 1.0044x over previous
.LBB0_28:
	s_andn2_b64 vcc, exec, s[0:1]
	s_cbranch_vccnz .LBB0_45
	v_readlane_b32 s4, v254, 42
	v_readlane_b32 s5, v254, 43
	s_mov_b32 s0, s35
	s_andn2_b64 vcc, exec, s[4:5]
	s_cbranch_vccnz .LBB0_45
	s_mov_b64 s[82:83], exec
	v_readlane_b32 s4, v254, 40
	v_readlane_b32 s5, v254, 41
	v_readlane_b32 s6, v255, 15
	v_readlane_b32 s7, v254, 21
	v_readlane_b32 s9, v255, 48
	v_readlane_b32 s10, v254, 34
	v_readlane_b32 s11, v254, 35
	s_nop 4
	s_load_dword s8, s[4:5], 0x0
	v_mbcnt_lo_u32_b32 v0, -1, 0
	v_mbcnt_hi_u32_b32 v0, -1, v0
	v_and_b32_e32 v1, 31, v0
	v_lshrrev_b32_e32 v2, 5, v0
	v_or_b32_e32 v3, s7, v0
	s_lshr_b32 s7, s7, 6
	s_and_b32 s9, s9, 0xff
	s_sub_u32 s9, s9, 2
	s_cmp_eq_u32 s9, 0
	s_mov_b32 s12, 0x3f077f5a
	s_mov_b32 s13, 0x3ee34c56
	s_cselect_b32 s12, s12, s13
	v_mul_u32_u24_e32 v4, 0x110, v1
	v_lshl_add_u32 v4, v2, 4, v4
	v_mul_u32_u24_e32 v5, 0x90, v1
	v_lshl_add_u32 v5, v2, 3, v5
	v_add_u32_e32 v5, 0x4400, v5
	v_lshrrev_b32_e32 v28, 4, v3
	v_and_b32_e32 v29, 15, v3
	v_lshlrev_b32_e32 v8, 11, v28
	v_lshl_add_u32 v8, v29, 4, v8
	v_add_u32_e32 v9, 0x8000, v8
	v_add_u32_e32 v10, 0x10000, v8
	v_add_u32_e32 v11, 0x18000, v8
	v_mul_u32_u24_e32 v16, 0x110, v28
	v_lshl_add_u32 v16, v29, 4, v16
	v_lshrrev_b32_e32 v28, 3, v3
	v_and_b32_e32 v29, 7, v3
	v_lshlrev_b32_e32 v12, 12, v28
	v_lshl_add_u32 v12, v29, 4, v12
	v_add_u32_e32 v13, 0x20000, v12
	v_add_u32_e32 v14, 0x40000, v12
	v_add_u32_e32 v15, 0x60000, v12
	v_mul_u32_u24_e32 v18, 0x90, v28
	v_lshl_add_u32 v18, v29, 4, v18
	v_add_u32_e32 v18, 0x4400, v18
	v_lshlrev_b32_e32 v26, 2, v0
	v_xor_b32_e32 v26, 0x80, v26
	v_mov_b32_e32 v27, 0xf149f2ca
	s_lshl_b32 s13, s7, 5
	v_add_u32_e32 v30, s13, v1
	v_lshlrev_b32_e32 v31, 11, v30
	v_lshl_add_u32 v31, v2, 4, v31
	s_lshl_b32 s13, s9, 9
	s_add_u32 s10, s10, s13
	s_addc_u32 s11, s11, 0
	v_lshlrev_b32_e32 v28, 4, v2
	global_load_dwordx4 a[160:163], v28, s[10:11] offset:0
	global_load_dwordx4 a[164:167], v28, s[10:11] offset:32
	global_load_dwordx4 a[168:171], v28, s[10:11] offset:64
	global_load_dwordx4 a[172:175], v28, s[10:11] offset:96
	global_load_dwordx4 a[176:179], v28, s[10:11] offset:128
	global_load_dwordx4 a[180:183], v28, s[10:11] offset:160
	global_load_dwordx4 a[184:187], v28, s[10:11] offset:192
	global_load_dwordx4 a[188:191], v28, s[10:11] offset:224
	global_load_dwordx4 a[192:195], v28, s[10:11] offset:256
	global_load_dwordx4 a[196:199], v28, s[10:11] offset:288
	global_load_dwordx4 a[200:203], v28, s[10:11] offset:320
	global_load_dwordx4 a[204:207], v28, s[10:11] offset:352
	global_load_dwordx4 a[208:211], v28, s[10:11] offset:384
	global_load_dwordx4 a[212:215], v28, s[10:11] offset:416
	global_load_dwordx4 a[216:219], v28, s[10:11] offset:448
	global_load_dwordx4 a[220:223], v28, s[10:11] offset:480
	s_lshl_b32 s13, s9, 2
	s_add_u32 s14, s92, s13
	s_addc_u32 s15, s93, 0
	v_mov_b32_e32 v28, 0x4020000
	global_load_dword v24, v28, s[14:15]
	s_waitcnt lgkmcnt(0)
	s_mov_b32 s22, s6
	s_cmp_ge_u32 s22, 0x800
	s_cbranch_scc1 .Lat_done
.Lat_item:
	s_lshr_b32 s13, s22, 7
	s_sub_u32 s13, 15, s13
	s_and_b32 s14, s22, 0x7f
	s_lshr_b32 s15, s14, 3
	s_and_b32 s14, s14, 7
	s_lshl_b32 s16, s13, 7
	s_lshl_b32 s17, s13, 1
	s_add_u32 s17, s17, 2
	s_lshl_b32 s19, s15, 11
	s_add_u32 s19, s19, s16
	s_lshl_b32 s20, s19, 11
	s_lshl_b32 s21, s14, 8
	s_add_u32 s20, s20, s21
	s_add_u32 s76, s92, 0x16100000
	s_addc_u32 s77, s93, 0
	s_add_u32 s76, s76, s20
	s_addc_u32 s77, s77, 0
	global_load_dwordx4 a[0:3], v31, s[76:77] offset:0
	global_load_dwordx4 a[4:7], v31, s[76:77] offset:32
	global_load_dwordx4 a[8:11], v31, s[76:77] offset:64
	global_load_dwordx4 a[12:15], v31, s[76:77] offset:96
	global_load_dwordx4 a[16:19], v31, s[76:77] offset:128
	global_load_dwordx4 a[20:23], v31, s[76:77] offset:160
	global_load_dwordx4 a[24:27], v31, s[76:77] offset:192
	global_load_dwordx4 a[28:31], v31, s[76:77] offset:224
	s_lshl_b32 s20, s15, 22
	s_add_u32 s20, s20, s21
	s_add_u32 s78, s92, 0x1a100000
	s_addc_u32 s79, s93, 0
	s_add_u32 s78, s78, s20
	s_addc_u32 s79, s79, 0
	s_lshl_b32 s20, s15, 3
	s_add_u32 s20, s20, s14
	s_lshl_b32 s20, s20, 19
	s_add_u32 s80, s92, 0x1e100000
	s_addc_u32 s81, s93, 0
	s_add_u32 s80, s80, s20
	s_addc_u32 s81, s81, 0
	global_load_dwordx4 a[224:227], v8, s[78:79]
	global_load_dwordx4 a[228:231], v9, s[78:79]
	global_load_dwordx4 a[232:235], v10, s[78:79]
	global_load_dwordx4 a[236:239], v11, s[78:79]
	global_load_dwordx4 a[240:243], v12, s[80:81]
	global_load_dwordx4 a[244:247], v13, s[80:81]
	global_load_dwordx4 a[248:251], v14, s[80:81]
	global_load_dwordx4 a[252:255], v15, s[80:81]
	v_mov_b32_e32 v64, 0
	v_mov_b32_e32 v65, 0
	v_mov_b32_e32 v66, 0
	v_mov_b32_e32 v67, 0
	v_mov_b32_e32 v68, 0
	v_mov_b32_e32 v69, 0
	v_mov_b32_e32 v70, 0
	v_mov_b32_e32 v71, 0
	v_mov_b32_e32 v72, 0
	v_mov_b32_e32 v73, 0
	v_mov_b32_e32 v74, 0
	v_mov_b32_e32 v75, 0
	v_mov_b32_e32 v76, 0
	v_mov_b32_e32 v77, 0
	v_mov_b32_e32 v78, 0
	v_mov_b32_e32 v79, 0
	v_mov_b32_e32 v80, 0
	v_mov_b32_e32 v81, 0
	v_mov_b32_e32 v82, 0
	v_mov_b32_e32 v83, 0
	v_mov_b32_e32 v84, 0
	v_mov_b32_e32 v85, 0
	v_mov_b32_e32 v86, 0
	v_mov_b32_e32 v87, 0
	v_mov_b32_e32 v88, 0
	v_mov_b32_e32 v89, 0
	v_mov_b32_e32 v90, 0
	v_mov_b32_e32 v91, 0
	v_mov_b32_e32 v92, 0
	v_mov_b32_e32 v93, 0
	v_mov_b32_e32 v94, 0
	v_mov_b32_e32 v95, 0
	v_mov_b32_e32 v96, 0
	v_mov_b32_e32 v97, 0
	v_mov_b32_e32 v98, 0
	v_mov_b32_e32 v99, 0
	v_mov_b32_e32 v100, 0
	v_mov_b32_e32 v101, 0
	v_mov_b32_e32 v102, 0
	v_mov_b32_e32 v103, 0
	v_mov_b32_e32 v104, 0
	v_mov_b32_e32 v105, 0
	v_mov_b32_e32 v106, 0
	v_mov_b32_e32 v107, 0
	v_mov_b32_e32 v108, 0
	v_mov_b32_e32 v109, 0
	v_mov_b32_e32 v110, 0
	v_mov_b32_e32 v111, 0
	v_mov_b32_e32 v112, 0
	v_mov_b32_e32 v113, 0
	v_mov_b32_e32 v114, 0
	v_mov_b32_e32 v115, 0
	v_mov_b32_e32 v116, 0
	v_mov_b32_e32 v117, 0
	v_mov_b32_e32 v118, 0
	v_mov_b32_e32 v119, 0
	v_mov_b32_e32 v120, 0
	v_mov_b32_e32 v121, 0
	v_mov_b32_e32 v122, 0
	v_mov_b32_e32 v123, 0
	v_mov_b32_e32 v124, 0
	v_mov_b32_e32 v125, 0
	v_mov_b32_e32 v126, 0
	v_mov_b32_e32 v127, 0
	v_mov_b32_e32 v128, 0
	v_mov_b32_e32 v129, 0
	v_mov_b32_e32 v130, 0
	v_mov_b32_e32 v131, 0
	v_mov_b32_e32 v132, 0
	v_mov_b32_e32 v133, 0
	v_mov_b32_e32 v134, 0
	v_mov_b32_e32 v135, 0
	v_mov_b32_e32 v136, 0
	v_mov_b32_e32 v137, 0
	v_mov_b32_e32 v138, 0
	v_mov_b32_e32 v139, 0
	v_mov_b32_e32 v140, 0
	v_mov_b32_e32 v141, 0
	v_mov_b32_e32 v142, 0
	v_mov_b32_e32 v143, 0
	v_mov_b32_e32 v144, 0
	v_mov_b32_e32 v145, 0
	v_mov_b32_e32 v146, 0
	v_mov_b32_e32 v147, 0
	v_mov_b32_e32 v148, 0
	v_mov_b32_e32 v149, 0
	v_mov_b32_e32 v150, 0
	v_mov_b32_e32 v151, 0
	v_mov_b32_e32 v152, 0
	v_mov_b32_e32 v153, 0
	v_mov_b32_e32 v154, 0
	v_mov_b32_e32 v155, 0
	v_mov_b32_e32 v156, 0
	v_mov_b32_e32 v157, 0
	v_mov_b32_e32 v158, 0
	v_mov_b32_e32 v159, 0
	v_mov_b32_e32 v160, 0
	v_mov_b32_e32 v161, 0
	v_mov_b32_e32 v162, 0
	v_mov_b32_e32 v163, 0
	v_mov_b32_e32 v164, 0
	v_mov_b32_e32 v165, 0
	v_mov_b32_e32 v166, 0
	v_mov_b32_e32 v167, 0
	v_mov_b32_e32 v168, 0
	v_mov_b32_e32 v169, 0
	v_mov_b32_e32 v170, 0
	v_mov_b32_e32 v171, 0
	v_mov_b32_e32 v172, 0
	v_mov_b32_e32 v173, 0
	v_mov_b32_e32 v174, 0
	v_mov_b32_e32 v175, 0
	v_mov_b32_e32 v176, 0
	v_mov_b32_e32 v177, 0
	v_mov_b32_e32 v178, 0
	v_mov_b32_e32 v179, 0
	v_mov_b32_e32 v180, 0
	v_mov_b32_e32 v181, 0
	v_mov_b32_e32 v182, 0
	v_mov_b32_e32 v183, 0
	v_mov_b32_e32 v184, 0
	v_mov_b32_e32 v185, 0
	v_mov_b32_e32 v186, 0
	v_mov_b32_e32 v187, 0
	v_mov_b32_e32 v188, 0
	v_mov_b32_e32 v189, 0
	v_mov_b32_e32 v190, 0
	v_mov_b32_e32 v191, 0
	v_mov_b32_e32 v20, v27
	v_mov_b32_e32 v21, v27
	v_mov_b32_e32 v22, 0
	v_mov_b32_e32 v23, 0
	v_add_u32_e32 v25, s16, v30
	v_lshlrev_b32_e32 v28, 2, v2
	v_sub_u32_e32 v25, v25, v28
	s_lshl_b32 s84, s7, 5
	s_add_u32 s84, s84, s16
	s_mov_b32 s85, 0
	s_mov_b32 s86, 0
	s_mov_b32 s87, 0
	s_barrier
	s_waitcnt vmcnt(0)
	ds_write_b128 v16, a[224:227] offset:0
	ds_write_b128 v16, a[228:231] offset:4352
	ds_write_b128 v16, a[232:235] offset:8704
	ds_write_b128 v16, a[236:239] offset:13056
	ds_write_b128 v18, a[240:243] offset:0
	ds_write_b128 v18, a[244:247] offset:4608
	ds_write_b128 v18, a[248:251] offset:9216
	ds_write_b128 v18, a[252:255] offset:13824
	s_waitcnt lgkmcnt(0)
	s_barrier
.Lat_kb:
	s_add_u32 s88, s86, 1
	s_sub_u32 s89, s17, 1
	s_min_u32 s88, s88, s89
	s_lshl_b32 s89, s88, 17
	s_add_u32 s90, s78, s89
	s_addc_u32 s91, s79, 0
	global_load_dwordx4 a[224:227], v8, s[90:91]
	global_load_dwordx4 a[228:231], v9, s[90:91]
	global_load_dwordx4 a[232:235], v10, s[90:91]
	global_load_dwordx4 a[236:239], v11, s[90:91]
	s_lshl_b32 s89, s88, 7
	s_add_u32 s90, s80, s89
	s_addc_u32 s91, s81, 0
	global_load_dwordx4 a[240:243], v12, s[90:91]
	global_load_dwordx4 a[244:247], v13, s[90:91]
	global_load_dwordx4 a[248:251], v14, s[90:91]
	global_load_dwordx4 a[252:255], v15, s[90:91]
	s_add_u32 s88, s84, 31
	s_cmp_gt_u32 s85, s88
	s_cbranch_scc1 .Lat_skip
	v_add_u32_e32 v6, s87, v4
	v_add_u32_e32 v7, s87, v5
	ds_read2_b64 a[96:99], v7 offset0:0 offset1:2
	ds_read2_b64 a[100:103], v7 offset0:4 offset1:6
	ds_read2_b64 a[128:131], v7 offset0:8 offset1:10
	ds_read2_b64 a[132:135], v7 offset0:12 offset1:14
	v_add_u32_e32 v28, 0x1200, v7
	ds_read2_b64 a[104:107], v28 offset0:0 offset1:2
	ds_read2_b64 a[108:111], v28 offset0:4 offset1:6
	ds_read2_b64 a[136:139], v28 offset0:8 offset1:10
	ds_read2_b64 a[140:143], v28 offset0:12 offset1:14
	v_add_u32_e32 v28, 0x2400, v7
	ds_read2_b64 a[112:115], v28 offset0:0 offset1:2
	ds_read2_b64 a[116:119], v28 offset0:4 offset1:6
	ds_read2_b64 a[144:147], v28 offset0:8 offset1:10
	ds_read2_b64 a[148:151], v28 offset0:12 offset1:14
	v_add_u32_e32 v28, 0x3600, v7
	ds_read2_b64 a[120:123], v28 offset0:0 offset1:2
	ds_read2_b64 a[124:127], v28 offset0:4 offset1:6
	ds_read2_b64 a[152:155], v28 offset0:8 offset1:10
	ds_read2_b64 a[156:159], v28 offset0:12 offset1:14
	ds_read_b128 a[32:35], v6 offset:0
	ds_read_b128 a[36:39], v6 offset:32
	ds_read_b128 a[40:43], v6 offset:64
	ds_read_b128 a[44:47], v6 offset:96
	ds_read_b128 a[48:51], v6 offset:8704
	ds_read_b128 a[52:55], v6 offset:8736
	ds_read_b128 a[56:59], v6 offset:8768
	ds_read_b128 a[60:63], v6 offset:8800
	ds_read_b128 a[64:67], v6 offset:128
	ds_read_b128 a[68:71], v6 offset:160
	ds_read_b128 a[72:75], v6 offset:192
	ds_read_b128 a[76:79], v6 offset:224
	ds_read_b128 a[80:83], v6 offset:8832
	ds_read_b128 a[84:87], v6 offset:8864
	ds_read_b128 a[88:91], v6 offset:8896
	ds_read_b128 a[92:95], v6 offset:8928
	s_add_u32 s88, s85, 63
	s_cmp_gt_u32 s88, s84
	s_cbranch_scc1 .Lat_diag
	s_waitcnt lgkmcnt(15)
	v_mfma_f32_32x32x16_bf16 v[192:207], a[32:35], a[0:3], 0
	s_waitcnt lgkmcnt(11)
	v_mfma_f32_32x32x16_bf16 v[208:223], a[48:51], a[0:3], 0
	s_waitcnt lgkmcnt(14)
	v_mfma_f32_32x32x16_bf16 v[192:207], a[36:39], a[4:7], v[192:207]
	s_waitcnt lgkmcnt(10)
	v_mfma_f32_32x32x16_bf16 v[208:223], a[52:55], a[4:7], v[208:223]
	s_waitcnt lgkmcnt(13)
	v_mfma_f32_32x32x16_bf16 v[192:207], a[40:43], a[8:11], v[192:207]
	s_waitcnt lgkmcnt(9)
	v_mfma_f32_32x32x16_bf16 v[208:223], a[56:59], a[8:11], v[208:223]
	s_waitcnt lgkmcnt(12)
	v_mfma_f32_32x32x16_bf16 v[192:207], a[44:47], a[12:15], v[192:207]
	s_waitcnt lgkmcnt(8)
	v_mfma_f32_32x32x16_bf16 v[208:223], a[60:63], a[12:15], v[208:223]
	s_waitcnt lgkmcnt(7)
	v_mfma_f32_32x32x16_bf16 v[32:47], a[64:67], a[16:19], 0
	s_waitcnt lgkmcnt(3)
	v_mfma_f32_32x32x16_bf16 v[48:63], a[80:83], a[16:19], 0
	s_waitcnt lgkmcnt(6)
	v_mfma_f32_32x32x16_bf16 v[32:47], a[68:71], a[20:23], v[32:47]
	s_waitcnt lgkmcnt(2)
	v_mfma_f32_32x32x16_bf16 v[48:63], a[84:87], a[20:23], v[48:63]
	s_nop 7
	s_waitcnt lgkmcnt(5)
	v_mfma_f32_32x32x16_bf16 v[32:47], a[72:75], a[24:27], v[32:47]
	v_max3_f32 v224, v192, v193, v194
	v_max3_f32 v224, v224, v195, v196
	v_max3_f32 v224, v224, v197, v198
	v_max3_f32 v224, v224, v199, v200
	v_max3_f32 v224, v224, v201, v202
	v_max3_f32 v224, v224, v203, v204
	v_max3_f32 v224, v224, v205, v206
	v_max3_f32 v224, v224, v207, v208
	s_waitcnt lgkmcnt(1)
	v_mfma_f32_32x32x16_bf16 v[48:63], a[88:91], a[24:27], v[48:63]
	v_max3_f32 v224, v224, v209, v210
	v_max3_f32 v224, v224, v211, v212
	v_max3_f32 v224, v224, v213, v214
	v_max3_f32 v224, v224, v215, v216
	v_max3_f32 v224, v224, v217, v218
	v_max3_f32 v224, v224, v219, v220
	v_max3_f32 v224, v224, v221, v222
	v_max_f32_e32 v224, v224, v223
	s_waitcnt lgkmcnt(4)
	v_mfma_f32_32x32x16_bf16 v[32:47], a[76:79], a[28:31], v[32:47]
	ds_bpermute_b32 v225, v26, v224
	s_waitcnt lgkmcnt(0)
	v_max3_f32 v226, v224, v225, v20
	v_sub_f32_e32 v228, v20, v226
	v_exp_f32_e32 v228, v228
	v_mov_b32_e32 v20, v226
	v_sub_f32_e32 v192, v192, v226
	v_sub_f32_e32 v193, v193, v226
	s_waitcnt lgkmcnt(0)
	v_mfma_f32_32x32x16_bf16 v[48:63], a[92:95], a[28:31], v[48:63]
	v_sub_f32_e32 v194, v194, v226
	v_sub_f32_e32 v195, v195, v226
	v_sub_f32_e32 v196, v196, v226
	v_sub_f32_e32 v197, v197, v226
	v_sub_f32_e32 v198, v198, v226
	v_sub_f32_e32 v199, v199, v226
	v_sub_f32_e32 v200, v200, v226
	v_sub_f32_e32 v201, v201, v226
	v_sub_f32_e32 v202, v202, v226
	v_sub_f32_e32 v203, v203, v226
	v_sub_f32_e32 v204, v204, v226
	v_sub_f32_e32 v205, v205, v226
	v_sub_f32_e32 v206, v206, v226
	v_sub_f32_e32 v207, v207, v226
	v_sub_f32_e32 v208, v208, v226
	v_sub_f32_e32 v209, v209, v226
	v_sub_f32_e32 v210, v210, v226
	v_sub_f32_e32 v211, v211, v226
	v_sub_f32_e32 v212, v212, v226
	v_sub_f32_e32 v213, v213, v226
	v_sub_f32_e32 v214, v214, v226
	v_sub_f32_e32 v215, v215, v226
	v_sub_f32_e32 v216, v216, v226
	v_sub_f32_e32 v217, v217, v226
	v_sub_f32_e32 v218, v218, v226
	v_sub_f32_e32 v219, v219, v226
	v_sub_f32_e32 v220, v220, v226
	v_sub_f32_e32 v221, v221, v226
	v_sub_f32_e32 v222, v222, v226
	v_sub_f32_e32 v223, v223, v226
	v_exp_f32_e32 v192, v192
	v_exp_f32_e32 v193, v193
	v_exp_f32_e32 v194, v194
	v_exp_f32_e32 v195, v195
	v_exp_f32_e32 v196, v196
	v_exp_f32_e32 v197, v197
	v_exp_f32_e32 v198, v198
	v_exp_f32_e32 v199, v199
	v_exp_f32_e32 v200, v200
	v_exp_f32_e32 v201, v201
	v_exp_f32_e32 v202, v202
	v_exp_f32_e32 v203, v203
	v_exp_f32_e32 v204, v204
	v_exp_f32_e32 v205, v205
	v_exp_f32_e32 v206, v206
	v_exp_f32_e32 v207, v207
	v_exp_f32_e32 v208, v208
	v_exp_f32_e32 v209, v209
	v_exp_f32_e32 v210, v210
	v_exp_f32_e32 v211, v211
	v_exp_f32_e32 v212, v212
	v_exp_f32_e32 v213, v213
	v_exp_f32_e32 v214, v214
	v_exp_f32_e32 v215, v215
	v_exp_f32_e32 v216, v216
	v_exp_f32_e32 v217, v217
	v_exp_f32_e32 v218, v218
	v_exp_f32_e32 v219, v219
	v_exp_f32_e32 v220, v220
	v_exp_f32_e32 v221, v221
	v_exp_f32_e32 v222, v222
	v_exp_f32_e32 v223, v223
	v_mul_f32_e32 v22, v22, v228
	v_add_f32_e32 v230, v192, v193
	v_add_f32_e32 v230, v230, v194
	v_add_f32_e32 v230, v230, v195
	v_add_f32_e32 v230, v230, v196
	v_add_f32_e32 v230, v230, v197
	v_add_f32_e32 v230, v230, v198
	v_add_f32_e32 v230, v230, v199
	v_add_f32_e32 v230, v230, v200
	v_add_f32_e32 v230, v230, v201
	v_add_f32_e32 v230, v230, v202
	v_add_f32_e32 v230, v230, v203
	v_add_f32_e32 v230, v230, v204
	v_add_f32_e32 v230, v230, v205
	v_add_f32_e32 v230, v230, v206
	v_add_f32_e32 v230, v230, v207
	v_add_f32_e32 v230, v230, v208
	v_add_f32_e32 v230, v230, v209
	v_add_f32_e32 v230, v230, v210
	v_add_f32_e32 v230, v230, v211
	v_add_f32_e32 v230, v230, v212
	v_add_f32_e32 v230, v230, v213
	v_add_f32_e32 v230, v230, v214
	v_add_f32_e32 v230, v230, v215
	v_add_f32_e32 v230, v230, v216
	v_add_f32_e32 v230, v230, v217
	v_add_f32_e32 v230, v230, v218
	v_add_f32_e32 v230, v230, v219
	v_add_f32_e32 v230, v230, v220
	v_add_f32_e32 v230, v230, v221
	v_add_f32_e32 v230, v230, v222
	v_add_f32_e32 v230, v230, v223
	v_add_f32_e32 v22, v22, v230
	v_pk_mul_f32 v[64:65], v[64:65], v[228:229] op_sel_hi:[1,0]
	v_pk_mul_f32 v[66:67], v[66:67], v[228:229] op_sel_hi:[1,0]
	v_pk_mul_f32 v[68:69], v[68:69], v[228:229] op_sel_hi:[1,0]
	v_pk_mul_f32 v[70:71], v[70:71], v[228:229] op_sel_hi:[1,0]
	v_pk_mul_f32 v[72:73], v[72:73], v[228:229] op_sel_hi:[1,0]
	v_pk_mul_f32 v[74:75], v[74:75], v[228:229] op_sel_hi:[1,0]
	v_pk_mul_f32 v[76:77], v[76:77], v[228:229] op_sel_hi:[1,0]
	v_pk_mul_f32 v[78:79], v[78:79], v[228:229] op_sel_hi:[1,0]
	v_pk_mul_f32 v[80:81], v[80:81], v[228:229] op_sel_hi:[1,0]
	v_pk_mul_f32 v[82:83], v[82:83], v[228:229] op_sel_hi:[1,0]
	v_pk_mul_f32 v[84:85], v[84:85], v[228:229] op_sel_hi:[1,0]
	v_pk_mul_f32 v[86:87], v[86:87], v[228:229] op_sel_hi:[1,0]
	v_pk_mul_f32 v[88:89], v[88:89], v[228:229] op_sel_hi:[1,0]
	v_pk_mul_f32 v[90:91], v[90:91], v[228:229] op_sel_hi:[1,0]
	v_pk_mul_f32 v[92:93], v[92:93], v[228:229] op_sel_hi:[1,0]
	v_pk_mul_f32 v[94:95], v[94:95], v[228:229] op_sel_hi:[1,0]
	v_pk_mul_f32 v[96:97], v[96:97], v[228:229] op_sel_hi:[1,0]
	v_pk_mul_f32 v[98:99], v[98:99], v[228:229] op_sel_hi:[1,0]
	v_pk_mul_f32 v[100:101], v[100:101], v[228:229] op_sel_hi:[1,0]
	v_pk_mul_f32 v[102:103], v[102:103], v[228:229] op_sel_hi:[1,0]
	v_pk_mul_f32 v[104:105], v[104:105], v[228:229] op_sel_hi:[1,0]
	v_pk_mul_f32 v[106:107], v[106:107], v[228:229] op_sel_hi:[1,0]
	v_pk_mul_f32 v[108:109], v[108:109], v[228:229] op_sel_hi:[1,0]
	v_pk_mul_f32 v[110:111], v[110:111], v[228:229] op_sel_hi:[1,0]
	v_pk_mul_f32 v[112:113], v[112:113], v[228:229] op_sel_hi:[1,0]
	v_pk_mul_f32 v[114:115], v[114:115], v[228:229] op_sel_hi:[1,0]
	v_pk_mul_f32 v[116:117], v[116:117], v[228:229] op_sel_hi:[1,0]
	v_pk_mul_f32 v[118:119], v[118:119], v[228:229] op_sel_hi:[1,0]
	v_pk_mul_f32 v[120:121], v[120:121], v[228:229] op_sel_hi:[1,0]
	v_pk_mul_f32 v[122:123], v[122:123], v[228:229] op_sel_hi:[1,0]
	v_pk_mul_f32 v[124:125], v[124:125], v[228:229] op_sel_hi:[1,0]
	v_pk_mul_f32 v[126:127], v[126:127], v[228:229] op_sel_hi:[1,0]
	v_cvt_pk_bf16_f32 v192, v192, v193
	v_cvt_pk_bf16_f32 v193, v194, v195
	v_cvt_pk_bf16_f32 v194, v196, v197
	v_cvt_pk_bf16_f32 v195, v198, v199
	v_cvt_pk_bf16_f32 v196, v200, v201
	v_cvt_pk_bf16_f32 v197, v202, v203
	v_cvt_pk_bf16_f32 v198, v204, v205
	v_cvt_pk_bf16_f32 v199, v206, v207
	v_cvt_pk_bf16_f32 v208, v208, v209
	v_cvt_pk_bf16_f32 v209, v210, v211
	v_cvt_pk_bf16_f32 v210, v212, v213
	v_cvt_pk_bf16_f32 v211, v214, v215
	v_cvt_pk_bf16_f32 v212, v216, v217
	v_cvt_pk_bf16_f32 v213, v218, v219
	v_cvt_pk_bf16_f32 v214, v220, v221
	v_cvt_pk_bf16_f32 v215, v222, v223
	s_nop 1
	v_mfma_f32_32x32x16_bf16 v[64:79], a[96:99], v[192:195], v[64:79]
	v_max3_f32 v232, v32, v33, v34
	v_max3_f32 v232, v232, v35, v36
	v_max3_f32 v232, v232, v37, v38
	v_max3_f32 v232, v232, v39, v40
	v_max3_f32 v232, v232, v41, v42
	v_max3_f32 v232, v232, v43, v44
	v_max3_f32 v232, v232, v45, v46
	v_max3_f32 v232, v232, v47, v48
	v_mfma_f32_32x32x16_bf16 v[64:79], a[100:103], v[196:199], v[64:79]
	v_max3_f32 v232, v232, v49, v50
	v_max3_f32 v232, v232, v51, v52
	v_max3_f32 v232, v232, v53, v54
	v_max3_f32 v232, v232, v55, v56
	v_max3_f32 v232, v232, v57, v58
	v_max3_f32 v232, v232, v59, v60
	v_max3_f32 v232, v232, v61, v62
	v_max_f32_e32 v232, v232, v63
	v_mfma_f32_32x32x16_bf16 v[80:95], a[104:107], v[192:195], v[80:95]
	ds_bpermute_b32 v233, v26, v232
	s_waitcnt lgkmcnt(0)
	v_max3_f32 v234, v232, v233, v21
	v_sub_f32_e32 v236, v21, v234
	v_exp_f32_e32 v236, v236
	v_mov_b32_e32 v21, v234
	v_sub_f32_e32 v32, v32, v234
	v_sub_f32_e32 v33, v33, v234
	v_mfma_f32_32x32x16_bf16 v[80:95], a[108:111], v[196:199], v[80:95]
	v_sub_f32_e32 v34, v34, v234
	v_sub_f32_e32 v35, v35, v234
	v_sub_f32_e32 v36, v36, v234
	v_sub_f32_e32 v37, v37, v234
	v_sub_f32_e32 v38, v38, v234
	v_sub_f32_e32 v39, v39, v234
	v_sub_f32_e32 v40, v40, v234
	v_sub_f32_e32 v41, v41, v234
	v_mfma_f32_32x32x16_bf16 v[96:111], a[112:115], v[192:195], v[96:111]
	v_sub_f32_e32 v42, v42, v234
	v_sub_f32_e32 v43, v43, v234
	v_sub_f32_e32 v44, v44, v234
	v_sub_f32_e32 v45, v45, v234
	v_sub_f32_e32 v46, v46, v234
	v_sub_f32_e32 v47, v47, v234
	v_sub_f32_e32 v48, v48, v234
	v_sub_f32_e32 v49, v49, v234
	v_mfma_f32_32x32x16_bf16 v[96:111], a[116:119], v[196:199], v[96:111]
	v_sub_f32_e32 v50, v50, v234
	v_sub_f32_e32 v51, v51, v234
	v_sub_f32_e32 v52, v52, v234
	v_sub_f32_e32 v53, v53, v234
	v_sub_f32_e32 v54, v54, v234
	v_sub_f32_e32 v55, v55, v234
	v_sub_f32_e32 v56, v56, v234
	v_sub_f32_e32 v57, v57, v234
	v_mfma_f32_32x32x16_bf16 v[112:127], a[120:123], v[192:195], v[112:127]
	v_sub_f32_e32 v58, v58, v234
	v_sub_f32_e32 v59, v59, v234
	v_sub_f32_e32 v60, v60, v234
	v_sub_f32_e32 v61, v61, v234
	v_sub_f32_e32 v62, v62, v234
	v_sub_f32_e32 v63, v63, v234
	v_exp_f32_e32 v32, v32
	v_exp_f32_e32 v33, v33
	v_mfma_f32_32x32x16_bf16 v[112:127], a[124:127], v[196:199], v[112:127]
	v_exp_f32_e32 v34, v34
	v_exp_f32_e32 v35, v35
	v_exp_f32_e32 v36, v36
	v_exp_f32_e32 v37, v37
	v_exp_f32_e32 v38, v38
	v_exp_f32_e32 v39, v39
	v_exp_f32_e32 v40, v40
	v_exp_f32_e32 v41, v41
	v_mfma_f32_32x32x16_bf16 v[64:79], a[128:131], v[208:211], v[64:79]
	v_exp_f32_e32 v42, v42
	v_exp_f32_e32 v43, v43
	v_exp_f32_e32 v44, v44
	v_exp_f32_e32 v45, v45
	v_exp_f32_e32 v46, v46
	v_exp_f32_e32 v47, v47
	v_exp_f32_e32 v48, v48
	v_exp_f32_e32 v49, v49
	v_mfma_f32_32x32x16_bf16 v[64:79], a[132:135], v[212:215], v[64:79]
	v_exp_f32_e32 v50, v50
	v_exp_f32_e32 v51, v51
	v_exp_f32_e32 v52, v52
	v_exp_f32_e32 v53, v53
	v_exp_f32_e32 v54, v54
	v_exp_f32_e32 v55, v55
	v_exp_f32_e32 v56, v56
	v_exp_f32_e32 v57, v57
	v_mfma_f32_32x32x16_bf16 v[80:95], a[136:139], v[208:211], v[80:95]
	v_exp_f32_e32 v58, v58
	v_exp_f32_e32 v59, v59
	v_exp_f32_e32 v60, v60
	v_exp_f32_e32 v61, v61
	v_exp_f32_e32 v62, v62
	v_exp_f32_e32 v63, v63
	v_mul_f32_e32 v23, v23, v236
	v_add_f32_e32 v238, v32, v33
	v_mfma_f32_32x32x16_bf16 v[80:95], a[140:143], v[212:215], v[80:95]
	v_add_f32_e32 v238, v238, v34
	v_add_f32_e32 v238, v238, v35
	v_add_f32_e32 v238, v238, v36
	v_add_f32_e32 v238, v238, v37
	v_add_f32_e32 v238, v238, v38
	v_add_f32_e32 v238, v238, v39
	v_add_f32_e32 v238, v238, v40
	v_add_f32_e32 v238, v238, v41
	v_mfma_f32_32x32x16_bf16 v[96:111], a[144:147], v[208:211], v[96:111]
	v_add_f32_e32 v238, v238, v42
	v_add_f32_e32 v238, v238, v43
	v_add_f32_e32 v238, v238, v44
	v_add_f32_e32 v238, v238, v45
	v_add_f32_e32 v238, v238, v46
	v_add_f32_e32 v238, v238, v47
	v_add_f32_e32 v238, v238, v48
	v_add_f32_e32 v238, v238, v49
	v_mfma_f32_32x32x16_bf16 v[96:111], a[148:151], v[212:215], v[96:111]
	v_add_f32_e32 v238, v238, v50
	v_add_f32_e32 v238, v238, v51
	v_add_f32_e32 v238, v238, v52
	v_add_f32_e32 v238, v238, v53
	v_add_f32_e32 v238, v238, v54
	v_add_f32_e32 v238, v238, v55
	v_add_f32_e32 v238, v238, v56
	v_add_f32_e32 v238, v238, v57
	v_mfma_f32_32x32x16_bf16 v[112:127], a[152:155], v[208:211], v[112:127]
	v_add_f32_e32 v238, v238, v58
	v_add_f32_e32 v238, v238, v59
	v_add_f32_e32 v238, v238, v60
	v_add_f32_e32 v238, v238, v61
	v_add_f32_e32 v238, v238, v62
	v_add_f32_e32 v238, v238, v63
	v_add_f32_e32 v23, v23, v238
	v_pk_mul_f32 v[128:129], v[128:129], v[236:237] op_sel_hi:[1,0]
	v_mfma_f32_32x32x16_bf16 v[112:127], a[156:159], v[212:215], v[112:127]
	v_pk_mul_f32 v[130:131], v[130:131], v[236:237] op_sel_hi:[1,0]
	v_pk_mul_f32 v[132:133], v[132:133], v[236:237] op_sel_hi:[1,0]
	v_pk_mul_f32 v[134:135], v[134:135], v[236:237] op_sel_hi:[1,0]
	v_pk_mul_f32 v[136:137], v[136:137], v[236:237] op_sel_hi:[1,0]
	v_pk_mul_f32 v[138:139], v[138:139], v[236:237] op_sel_hi:[1,0]
	v_pk_mul_f32 v[140:141], v[140:141], v[236:237] op_sel_hi:[1,0]
	v_pk_mul_f32 v[142:143], v[142:143], v[236:237] op_sel_hi:[1,0]
	v_pk_mul_f32 v[144:145], v[144:145], v[236:237] op_sel_hi:[1,0]
	v_pk_mul_f32 v[146:147], v[146:147], v[236:237] op_sel_hi:[1,0]
	v_pk_mul_f32 v[148:149], v[148:149], v[236:237] op_sel_hi:[1,0]
	v_pk_mul_f32 v[150:151], v[150:151], v[236:237] op_sel_hi:[1,0]
	v_pk_mul_f32 v[152:153], v[152:153], v[236:237] op_sel_hi:[1,0]
	v_pk_mul_f32 v[154:155], v[154:155], v[236:237] op_sel_hi:[1,0]
	v_pk_mul_f32 v[156:157], v[156:157], v[236:237] op_sel_hi:[1,0]
	v_pk_mul_f32 v[158:159], v[158:159], v[236:237] op_sel_hi:[1,0]
	v_pk_mul_f32 v[160:161], v[160:161], v[236:237] op_sel_hi:[1,0]
	v_pk_mul_f32 v[162:163], v[162:163], v[236:237] op_sel_hi:[1,0]
	v_pk_mul_f32 v[164:165], v[164:165], v[236:237] op_sel_hi:[1,0]
	v_pk_mul_f32 v[166:167], v[166:167], v[236:237] op_sel_hi:[1,0]
	v_pk_mul_f32 v[168:169], v[168:169], v[236:237] op_sel_hi:[1,0]
	v_pk_mul_f32 v[170:171], v[170:171], v[236:237] op_sel_hi:[1,0]
	v_pk_mul_f32 v[172:173], v[172:173], v[236:237] op_sel_hi:[1,0]
	v_pk_mul_f32 v[174:175], v[174:175], v[236:237] op_sel_hi:[1,0]
	v_pk_mul_f32 v[176:177], v[176:177], v[236:237] op_sel_hi:[1,0]
	v_pk_mul_f32 v[178:179], v[178:179], v[236:237] op_sel_hi:[1,0]
	v_pk_mul_f32 v[180:181], v[180:181], v[236:237] op_sel_hi:[1,0]
	v_pk_mul_f32 v[182:183], v[182:183], v[236:237] op_sel_hi:[1,0]
	v_pk_mul_f32 v[184:185], v[184:185], v[236:237] op_sel_hi:[1,0]
	v_pk_mul_f32 v[186:187], v[186:187], v[236:237] op_sel_hi:[1,0]
	v_pk_mul_f32 v[188:189], v[188:189], v[236:237] op_sel_hi:[1,0]
	v_pk_mul_f32 v[190:191], v[190:191], v[236:237] op_sel_hi:[1,0]
	v_cvt_pk_bf16_f32 v32, v32, v33
	v_cvt_pk_bf16_f32 v33, v34, v35
	v_cvt_pk_bf16_f32 v34, v36, v37
	v_cvt_pk_bf16_f32 v35, v38, v39
	v_cvt_pk_bf16_f32 v36, v40, v41
	v_cvt_pk_bf16_f32 v37, v42, v43
	v_cvt_pk_bf16_f32 v38, v44, v45
	v_cvt_pk_bf16_f32 v39, v46, v47
	v_cvt_pk_bf16_f32 v48, v48, v49
	v_cvt_pk_bf16_f32 v49, v50, v51
	v_cvt_pk_bf16_f32 v50, v52, v53
	v_cvt_pk_bf16_f32 v51, v54, v55
	v_cvt_pk_bf16_f32 v52, v56, v57
	v_cvt_pk_bf16_f32 v53, v58, v59
	v_cvt_pk_bf16_f32 v54, v60, v61
	v_cvt_pk_bf16_f32 v55, v62, v63
	s_nop 1
	v_mfma_f32_32x32x16_bf16 v[128:143], a[96:99], v[32:35], v[128:143]
	v_mfma_f32_32x32x16_bf16 v[128:143], a[100:103], v[36:39], v[128:143]
	v_mfma_f32_32x32x16_bf16 v[144:159], a[104:107], v[32:35], v[144:159]
	v_mfma_f32_32x32x16_bf16 v[144:159], a[108:111], v[36:39], v[144:159]
	v_mfma_f32_32x32x16_bf16 v[160:175], a[112:115], v[32:35], v[160:175]
	v_mfma_f32_32x32x16_bf16 v[160:175], a[116:119], v[36:39], v[160:175]
	v_mfma_f32_32x32x16_bf16 v[176:191], a[120:123], v[32:35], v[176:191]
	v_mfma_f32_32x32x16_bf16 v[176:191], a[124:127], v[36:39], v[176:191]
	v_mfma_f32_32x32x16_bf16 v[128:143], a[128:131], v[48:51], v[128:143]
	v_mfma_f32_32x32x16_bf16 v[128:143], a[132:135], v[52:55], v[128:143]
	v_mfma_f32_32x32x16_bf16 v[144:159], a[136:139], v[48:51], v[144:159]
	v_mfma_f32_32x32x16_bf16 v[144:159], a[140:143], v[52:55], v[144:159]
	v_mfma_f32_32x32x16_bf16 v[160:175], a[144:147], v[48:51], v[160:175]
	v_mfma_f32_32x32x16_bf16 v[160:175], a[148:151], v[52:55], v[160:175]
	v_mfma_f32_32x32x16_bf16 v[176:191], a[152:155], v[48:51], v[176:191]
	v_mfma_f32_32x32x16_bf16 v[176:191], a[156:159], v[52:55], v[176:191]
	s_branch .Lat_skip
.Lat_diag:
	s_waitcnt lgkmcnt(15)
	v_mfma_f32_32x32x16_bf16 v[192:207], a[32:35], a[0:3], 0
	s_waitcnt lgkmcnt(11)
	v_mfma_f32_32x32x16_bf16 v[208:223], a[48:51], a[0:3], 0
	s_waitcnt lgkmcnt(14)
	v_mfma_f32_32x32x16_bf16 v[192:207], a[36:39], a[4:7], v[192:207]
	s_waitcnt lgkmcnt(10)
	v_mfma_f32_32x32x16_bf16 v[208:223], a[52:55], a[4:7], v[208:223]
	s_waitcnt lgkmcnt(13)
	v_mfma_f32_32x32x16_bf16 v[192:207], a[40:43], a[8:11], v[192:207]
	s_waitcnt lgkmcnt(9)
	v_mfma_f32_32x32x16_bf16 v[208:223], a[56:59], a[8:11], v[208:223]
	s_waitcnt lgkmcnt(12)
	v_mfma_f32_32x32x16_bf16 v[192:207], a[44:47], a[12:15], v[192:207]
	s_waitcnt lgkmcnt(8)
	v_mfma_f32_32x32x16_bf16 v[208:223], a[60:63], a[12:15], v[208:223]
	s_waitcnt lgkmcnt(7)
	v_mfma_f32_32x32x16_bf16 v[32:47], a[64:67], a[16:19], 0
	s_waitcnt lgkmcnt(3)
	v_mfma_f32_32x32x16_bf16 v[48:63], a[80:83], a[16:19], 0
	s_waitcnt lgkmcnt(6)
	v_mfma_f32_32x32x16_bf16 v[32:47], a[68:71], a[20:23], v[32:47]
	s_waitcnt lgkmcnt(2)
	v_mfma_f32_32x32x16_bf16 v[48:63], a[84:87], a[20:23], v[48:63]
	s_nop 7
	s_waitcnt lgkmcnt(5)
	v_mfma_f32_32x32x16_bf16 v[32:47], a[72:75], a[24:27], v[32:47]
	v_cmp_gt_i32_e64 s[0:1], 0, v25
	v_cmp_gt_i32_e64 s[4:5], 1, v25
	v_cmp_gt_i32_e64 s[10:11], 2, v25
	v_cmp_gt_i32_e64 s[20:21], 3, v25
	v_cndmask_b32_e64 v192, v192, v27, s[0:1]
	v_cndmask_b32_e64 v193, v193, v27, s[4:5]
	v_cndmask_b32_e64 v194, v194, v27, s[10:11]
	v_cndmask_b32_e64 v195, v195, v27, s[20:21]
	s_waitcnt lgkmcnt(1)
	v_mfma_f32_32x32x16_bf16 v[48:63], a[88:91], a[24:27], v[48:63]
	v_cmp_gt_i32_e64 s[0:1], 8, v25
	v_cmp_gt_i32_e64 s[4:5], 9, v25
	v_cmp_gt_i32_e64 s[10:11], 10, v25
	v_cmp_gt_i32_e64 s[20:21], 11, v25
	v_cndmask_b32_e64 v196, v196, v27, s[0:1]
	v_cndmask_b32_e64 v197, v197, v27, s[4:5]
	v_cndmask_b32_e64 v198, v198, v27, s[10:11]
	v_cndmask_b32_e64 v199, v199, v27, s[20:21]
	s_waitcnt lgkmcnt(4)
	v_mfma_f32_32x32x16_bf16 v[32:47], a[76:79], a[28:31], v[32:47]
	v_cmp_gt_i32_e64 s[0:1], 16, v25
	v_cmp_gt_i32_e64 s[4:5], 17, v25
	v_cmp_gt_i32_e64 s[10:11], 18, v25
	v_cmp_gt_i32_e64 s[20:21], 19, v25
	v_cndmask_b32_e64 v200, v200, v27, s[0:1]
	v_cndmask_b32_e64 v201, v201, v27, s[4:5]
	v_cndmask_b32_e64 v202, v202, v27, s[10:11]
	v_cndmask_b32_e64 v203, v203, v27, s[20:21]
	s_waitcnt lgkmcnt(0)
	v_mfma_f32_32x32x16_bf16 v[48:63], a[92:95], a[28:31], v[48:63]
	v_cmp_gt_i32_e64 s[0:1], 24, v25
	v_cmp_gt_i32_e64 s[4:5], 25, v25
	v_cmp_gt_i32_e64 s[10:11], 26, v25
	v_cmp_gt_i32_e64 s[20:21], 27, v25
	v_cndmask_b32_e64 v204, v204, v27, s[0:1]
	v_cndmask_b32_e64 v205, v205, v27, s[4:5]
	v_cndmask_b32_e64 v206, v206, v27, s[10:11]
	v_cndmask_b32_e64 v207, v207, v27, s[20:21]
	v_cmp_gt_i32_e64 s[0:1], 32, v25
	v_cmp_gt_i32_e64 s[4:5], 33, v25
	v_cmp_gt_i32_e64 s[10:11], 34, v25
	v_cmp_gt_i32_e64 s[20:21], 35, v25
	v_cndmask_b32_e64 v208, v208, v27, s[0:1]
	v_cndmask_b32_e64 v209, v209, v27, s[4:5]
	v_cndmask_b32_e64 v210, v210, v27, s[10:11]
	v_cndmask_b32_e64 v211, v211, v27, s[20:21]
	v_cmp_gt_i32_e64 s[0:1], 40, v25
	v_cmp_gt_i32_e64 s[4:5], 41, v25
	v_cmp_gt_i32_e64 s[10:11], 42, v25
	v_cmp_gt_i32_e64 s[20:21], 43, v25
	v_cndmask_b32_e64 v212, v212, v27, s[0:1]
	v_cndmask_b32_e64 v213, v213, v27, s[4:5]
	v_cndmask_b32_e64 v214, v214, v27, s[10:11]
	v_cndmask_b32_e64 v215, v215, v27, s[20:21]
	v_cmp_gt_i32_e64 s[0:1], 48, v25
	v_cmp_gt_i32_e64 s[4:5], 49, v25
	v_cmp_gt_i32_e64 s[10:11], 50, v25
	v_cmp_gt_i32_e64 s[20:21], 51, v25
	v_cndmask_b32_e64 v216, v216, v27, s[0:1]
	v_cndmask_b32_e64 v217, v217, v27, s[4:5]
	v_cndmask_b32_e64 v218, v218, v27, s[10:11]
	v_cndmask_b32_e64 v219, v219, v27, s[20:21]
	v_cmp_gt_i32_e64 s[0:1], 56, v25
	v_cmp_gt_i32_e64 s[4:5], 57, v25
	v_cmp_gt_i32_e64 s[10:11], 58, v25
	v_cmp_gt_i32_e64 s[20:21], 59, v25
	v_cndmask_b32_e64 v220, v220, v27, s[0:1]
	v_cndmask_b32_e64 v221, v221, v27, s[4:5]
	v_cndmask_b32_e64 v222, v222, v27, s[10:11]
	v_cndmask_b32_e64 v223, v223, v27, s[20:21]
	v_max3_f32 v224, v192, v193, v194
	v_max3_f32 v224, v224, v195, v196
	v_max3_f32 v224, v224, v197, v198
	v_max3_f32 v224, v224, v199, v200
	v_max3_f32 v224, v224, v201, v202
	v_max3_f32 v224, v224, v203, v204
	v_max3_f32 v224, v224, v205, v206
	v_max3_f32 v224, v224, v207, v208
	v_max3_f32 v224, v224, v209, v210
	v_max3_f32 v224, v224, v211, v212
	v_max3_f32 v224, v224, v213, v214
	v_max3_f32 v224, v224, v215, v216
	v_max3_f32 v224, v224, v217, v218
	v_max3_f32 v224, v224, v219, v220
	v_max3_f32 v224, v224, v221, v222
	v_max_f32_e32 v224, v224, v223
	ds_bpermute_b32 v225, v26, v224
	s_waitcnt lgkmcnt(0)
	v_max3_f32 v226, v224, v225, v20
	v_sub_f32_e32 v228, v20, v226
	v_exp_f32_e32 v228, v228
	v_mov_b32_e32 v20, v226
	v_sub_f32_e32 v192, v192, v226
	v_sub_f32_e32 v193, v193, v226
	v_sub_f32_e32 v194, v194, v226
	v_sub_f32_e32 v195, v195, v226
	v_sub_f32_e32 v196, v196, v226
	v_sub_f32_e32 v197, v197, v226
	v_sub_f32_e32 v198, v198, v226
	v_sub_f32_e32 v199, v199, v226
	v_sub_f32_e32 v200, v200, v226
	v_sub_f32_e32 v201, v201, v226
	v_sub_f32_e32 v202, v202, v226
	v_sub_f32_e32 v203, v203, v226
	v_sub_f32_e32 v204, v204, v226
	v_sub_f32_e32 v205, v205, v226
	v_sub_f32_e32 v206, v206, v226
	v_sub_f32_e32 v207, v207, v226
	v_sub_f32_e32 v208, v208, v226
	v_sub_f32_e32 v209, v209, v226
	v_sub_f32_e32 v210, v210, v226
	v_sub_f32_e32 v211, v211, v226
	v_sub_f32_e32 v212, v212, v226
	v_sub_f32_e32 v213, v213, v226
	v_sub_f32_e32 v214, v214, v226
	v_sub_f32_e32 v215, v215, v226
	v_sub_f32_e32 v216, v216, v226
	v_sub_f32_e32 v217, v217, v226
	v_sub_f32_e32 v218, v218, v226
	v_sub_f32_e32 v219, v219, v226
	v_sub_f32_e32 v220, v220, v226
	v_sub_f32_e32 v221, v221, v226
	v_sub_f32_e32 v222, v222, v226
	v_sub_f32_e32 v223, v223, v226
	v_exp_f32_e32 v192, v192
	v_exp_f32_e32 v193, v193
	v_exp_f32_e32 v194, v194
	v_exp_f32_e32 v195, v195
	v_exp_f32_e32 v196, v196
	v_exp_f32_e32 v197, v197
	v_exp_f32_e32 v198, v198
	v_exp_f32_e32 v199, v199
	v_exp_f32_e32 v200, v200
	v_exp_f32_e32 v201, v201
	v_exp_f32_e32 v202, v202
	v_exp_f32_e32 v203, v203
	v_exp_f32_e32 v204, v204
	v_exp_f32_e32 v205, v205
	v_exp_f32_e32 v206, v206
	v_exp_f32_e32 v207, v207
	v_exp_f32_e32 v208, v208
	v_exp_f32_e32 v209, v209
	v_exp_f32_e32 v210, v210
	v_exp_f32_e32 v211, v211
	v_exp_f32_e32 v212, v212
	v_exp_f32_e32 v213, v213
	v_exp_f32_e32 v214, v214
	v_exp_f32_e32 v215, v215
	v_exp_f32_e32 v216, v216
	v_exp_f32_e32 v217, v217
	v_exp_f32_e32 v218, v218
	v_exp_f32_e32 v219, v219
	v_exp_f32_e32 v220, v220
	v_exp_f32_e32 v221, v221
	v_exp_f32_e32 v222, v222
	v_exp_f32_e32 v223, v223
	v_mul_f32_e32 v22, v22, v228
	v_add_f32_e32 v230, v192, v193
	v_add_f32_e32 v230, v230, v194
	v_add_f32_e32 v230, v230, v195
	v_add_f32_e32 v230, v230, v196
	v_add_f32_e32 v230, v230, v197
	v_add_f32_e32 v230, v230, v198
	v_add_f32_e32 v230, v230, v199
	v_add_f32_e32 v230, v230, v200
	v_add_f32_e32 v230, v230, v201
	v_add_f32_e32 v230, v230, v202
	v_add_f32_e32 v230, v230, v203
	v_add_f32_e32 v230, v230, v204
	v_add_f32_e32 v230, v230, v205
	v_add_f32_e32 v230, v230, v206
	v_add_f32_e32 v230, v230, v207
	v_add_f32_e32 v230, v230, v208
	v_add_f32_e32 v230, v230, v209
	v_add_f32_e32 v230, v230, v210
	v_add_f32_e32 v230, v230, v211
	v_add_f32_e32 v230, v230, v212
	v_add_f32_e32 v230, v230, v213
	v_add_f32_e32 v230, v230, v214
	v_add_f32_e32 v230, v230, v215
	v_add_f32_e32 v230, v230, v216
	v_add_f32_e32 v230, v230, v217
	v_add_f32_e32 v230, v230, v218
	v_add_f32_e32 v230, v230, v219
	v_add_f32_e32 v230, v230, v220
	v_add_f32_e32 v230, v230, v221
	v_add_f32_e32 v230, v230, v222
	v_add_f32_e32 v230, v230, v223
	v_add_f32_e32 v22, v22, v230
	v_pk_mul_f32 v[64:65], v[64:65], v[228:229] op_sel_hi:[1,0]
	v_pk_mul_f32 v[66:67], v[66:67], v[228:229] op_sel_hi:[1,0]
	v_pk_mul_f32 v[68:69], v[68:69], v[228:229] op_sel_hi:[1,0]
	v_pk_mul_f32 v[70:71], v[70:71], v[228:229] op_sel_hi:[1,0]
	v_pk_mul_f32 v[72:73], v[72:73], v[228:229] op_sel_hi:[1,0]
	v_pk_mul_f32 v[74:75], v[74:75], v[228:229] op_sel_hi:[1,0]
	v_pk_mul_f32 v[76:77], v[76:77], v[228:229] op_sel_hi:[1,0]
	v_pk_mul_f32 v[78:79], v[78:79], v[228:229] op_sel_hi:[1,0]
	v_pk_mul_f32 v[80:81], v[80:81], v[228:229] op_sel_hi:[1,0]
	v_pk_mul_f32 v[82:83], v[82:83], v[228:229] op_sel_hi:[1,0]
	v_pk_mul_f32 v[84:85], v[84:85], v[228:229] op_sel_hi:[1,0]
	v_pk_mul_f32 v[86:87], v[86:87], v[228:229] op_sel_hi:[1,0]
	v_pk_mul_f32 v[88:89], v[88:89], v[228:229] op_sel_hi:[1,0]
	v_pk_mul_f32 v[90:91], v[90:91], v[228:229] op_sel_hi:[1,0]
	v_pk_mul_f32 v[92:93], v[92:93], v[228:229] op_sel_hi:[1,0]
	v_pk_mul_f32 v[94:95], v[94:95], v[228:229] op_sel_hi:[1,0]
	v_pk_mul_f32 v[96:97], v[96:97], v[228:229] op_sel_hi:[1,0]
	v_pk_mul_f32 v[98:99], v[98:99], v[228:229] op_sel_hi:[1,0]
	v_pk_mul_f32 v[100:101], v[100:101], v[228:229] op_sel_hi:[1,0]
	v_pk_mul_f32 v[102:103], v[102:103], v[228:229] op_sel_hi:[1,0]
	v_pk_mul_f32 v[104:105], v[104:105], v[228:229] op_sel_hi:[1,0]
	v_pk_mul_f32 v[106:107], v[106:107], v[228:229] op_sel_hi:[1,0]
	v_pk_mul_f32 v[108:109], v[108:109], v[228:229] op_sel_hi:[1,0]
	v_pk_mul_f32 v[110:111], v[110:111], v[228:229] op_sel_hi:[1,0]
	v_pk_mul_f32 v[112:113], v[112:113], v[228:229] op_sel_hi:[1,0]
	v_pk_mul_f32 v[114:115], v[114:115], v[228:229] op_sel_hi:[1,0]
	v_pk_mul_f32 v[116:117], v[116:117], v[228:229] op_sel_hi:[1,0]
	v_pk_mul_f32 v[118:119], v[118:119], v[228:229] op_sel_hi:[1,0]
	v_pk_mul_f32 v[120:121], v[120:121], v[228:229] op_sel_hi:[1,0]
	v_pk_mul_f32 v[122:123], v[122:123], v[228:229] op_sel_hi:[1,0]
	v_pk_mul_f32 v[124:125], v[124:125], v[228:229] op_sel_hi:[1,0]
	v_pk_mul_f32 v[126:127], v[126:127], v[228:229] op_sel_hi:[1,0]
	v_cvt_pk_bf16_f32 v192, v192, v193
	v_cvt_pk_bf16_f32 v193, v194, v195
	v_cvt_pk_bf16_f32 v194, v196, v197
	v_cvt_pk_bf16_f32 v195, v198, v199
	v_cvt_pk_bf16_f32 v196, v200, v201
	v_cvt_pk_bf16_f32 v197, v202, v203
	v_cvt_pk_bf16_f32 v198, v204, v205
	v_cvt_pk_bf16_f32 v199, v206, v207
	v_cvt_pk_bf16_f32 v208, v208, v209
	v_cvt_pk_bf16_f32 v209, v210, v211
	v_cvt_pk_bf16_f32 v210, v212, v213
	v_cvt_pk_bf16_f32 v211, v214, v215
	v_cvt_pk_bf16_f32 v212, v216, v217
	v_cvt_pk_bf16_f32 v213, v218, v219
	v_cvt_pk_bf16_f32 v214, v220, v221
	v_cvt_pk_bf16_f32 v215, v222, v223
	s_nop 1
	v_mfma_f32_32x32x16_bf16 v[64:79], a[96:99], v[192:195], v[64:79]
	v_cmp_gt_i32_e64 s[0:1], 0, v25
	v_cmp_gt_i32_e64 s[4:5], 1, v25
	v_cmp_gt_i32_e64 s[10:11], 2, v25
	v_cmp_gt_i32_e64 s[20:21], 3, v25
	v_cndmask_b32_e64 v32, v32, v27, s[0:1]
	v_cndmask_b32_e64 v33, v33, v27, s[4:5]
	v_cndmask_b32_e64 v34, v34, v27, s[10:11]
	v_cndmask_b32_e64 v35, v35, v27, s[20:21]
	v_mfma_f32_32x32x16_bf16 v[64:79], a[100:103], v[196:199], v[64:79]
	v_cmp_gt_i32_e64 s[0:1], 8, v25
	v_cmp_gt_i32_e64 s[4:5], 9, v25
	v_cmp_gt_i32_e64 s[10:11], 10, v25
	v_cmp_gt_i32_e64 s[20:21], 11, v25
	v_cndmask_b32_e64 v36, v36, v27, s[0:1]
	v_cndmask_b32_e64 v37, v37, v27, s[4:5]
	v_cndmask_b32_e64 v38, v38, v27, s[10:11]
	v_cndmask_b32_e64 v39, v39, v27, s[20:21]
	v_mfma_f32_32x32x16_bf16 v[80:95], a[104:107], v[192:195], v[80:95]
	v_cmp_gt_i32_e64 s[0:1], 16, v25
	v_cmp_gt_i32_e64 s[4:5], 17, v25
	v_cmp_gt_i32_e64 s[10:11], 18, v25
	v_cmp_gt_i32_e64 s[20:21], 19, v25
	v_cndmask_b32_e64 v40, v40, v27, s[0:1]
	v_cndmask_b32_e64 v41, v41, v27, s[4:5]
	v_cndmask_b32_e64 v42, v42, v27, s[10:11]
	v_cndmask_b32_e64 v43, v43, v27, s[20:21]
	v_mfma_f32_32x32x16_bf16 v[80:95], a[108:111], v[196:199], v[80:95]
	v_cmp_gt_i32_e64 s[0:1], 24, v25
	v_cmp_gt_i32_e64 s[4:5], 25, v25
	v_cmp_gt_i32_e64 s[10:11], 26, v25
	v_cmp_gt_i32_e64 s[20:21], 27, v25
	v_cndmask_b32_e64 v44, v44, v27, s[0:1]
	v_cndmask_b32_e64 v45, v45, v27, s[4:5]
	v_cndmask_b32_e64 v46, v46, v27, s[10:11]
	v_cndmask_b32_e64 v47, v47, v27, s[20:21]
	v_mfma_f32_32x32x16_bf16 v[96:111], a[112:115], v[192:195], v[96:111]
	v_cmp_gt_i32_e64 s[0:1], 32, v25
	v_cmp_gt_i32_e64 s[4:5], 33, v25
	v_cmp_gt_i32_e64 s[10:11], 34, v25
	v_cmp_gt_i32_e64 s[20:21], 35, v25
	v_cndmask_b32_e64 v48, v48, v27, s[0:1]
	v_cndmask_b32_e64 v49, v49, v27, s[4:5]
	v_cndmask_b32_e64 v50, v50, v27, s[10:11]
	v_cndmask_b32_e64 v51, v51, v27, s[20:21]
	v_mfma_f32_32x32x16_bf16 v[96:111], a[116:119], v[196:199], v[96:111]
	v_cmp_gt_i32_e64 s[0:1], 40, v25
	v_cmp_gt_i32_e64 s[4:5], 41, v25
	v_cmp_gt_i32_e64 s[10:11], 42, v25
	v_cmp_gt_i32_e64 s[20:21], 43, v25
	v_cndmask_b32_e64 v52, v52, v27, s[0:1]
	v_cndmask_b32_e64 v53, v53, v27, s[4:5]
	v_cndmask_b32_e64 v54, v54, v27, s[10:11]
	v_cndmask_b32_e64 v55, v55, v27, s[20:21]
	v_mfma_f32_32x32x16_bf16 v[112:127], a[120:123], v[192:195], v[112:127]
	v_cmp_gt_i32_e64 s[0:1], 48, v25
	v_cmp_gt_i32_e64 s[4:5], 49, v25
	v_cmp_gt_i32_e64 s[10:11], 50, v25
	v_cmp_gt_i32_e64 s[20:21], 51, v25
	v_cndmask_b32_e64 v56, v56, v27, s[0:1]
	v_cndmask_b32_e64 v57, v57, v27, s[4:5]
	v_cndmask_b32_e64 v58, v58, v27, s[10:11]
	v_cndmask_b32_e64 v59, v59, v27, s[20:21]
	v_mfma_f32_32x32x16_bf16 v[112:127], a[124:127], v[196:199], v[112:127]
	v_cmp_gt_i32_e64 s[0:1], 56, v25
	v_cmp_gt_i32_e64 s[4:5], 57, v25
	v_cmp_gt_i32_e64 s[10:11], 58, v25
	v_cmp_gt_i32_e64 s[20:21], 59, v25
	v_cndmask_b32_e64 v60, v60, v27, s[0:1]
	v_cndmask_b32_e64 v61, v61, v27, s[4:5]
	v_cndmask_b32_e64 v62, v62, v27, s[10:11]
	v_cndmask_b32_e64 v63, v63, v27, s[20:21]
	v_mfma_f32_32x32x16_bf16 v[64:79], a[128:131], v[208:211], v[64:79]
	v_max3_f32 v232, v32, v33, v34
	v_max3_f32 v232, v232, v35, v36
	v_max3_f32 v232, v232, v37, v38
	v_max3_f32 v232, v232, v39, v40
	v_max3_f32 v232, v232, v41, v42
	v_max3_f32 v232, v232, v43, v44
	v_max3_f32 v232, v232, v45, v46
	v_max3_f32 v232, v232, v47, v48
	v_mfma_f32_32x32x16_bf16 v[64:79], a[132:135], v[212:215], v[64:79]
	v_max3_f32 v232, v232, v49, v50
	v_max3_f32 v232, v232, v51, v52
	v_max3_f32 v232, v232, v53, v54
	v_max3_f32 v232, v232, v55, v56
	v_max3_f32 v232, v232, v57, v58
	v_max3_f32 v232, v232, v59, v60
	v_max3_f32 v232, v232, v61, v62
	v_max_f32_e32 v232, v232, v63
	v_mfma_f32_32x32x16_bf16 v[80:95], a[136:139], v[208:211], v[80:95]
	ds_bpermute_b32 v233, v26, v232
	s_waitcnt lgkmcnt(0)
	v_max3_f32 v234, v232, v233, v21
	v_sub_f32_e32 v236, v21, v234
	v_exp_f32_e32 v236, v236
	v_mov_b32_e32 v21, v234
	v_sub_f32_e32 v32, v32, v234
	v_sub_f32_e32 v33, v33, v234
	v_mfma_f32_32x32x16_bf16 v[80:95], a[140:143], v[212:215], v[80:95]
	v_sub_f32_e32 v34, v34, v234
	v_sub_f32_e32 v35, v35, v234
	v_sub_f32_e32 v36, v36, v234
	v_sub_f32_e32 v37, v37, v234
	v_sub_f32_e32 v38, v38, v234
	v_sub_f32_e32 v39, v39, v234
	v_sub_f32_e32 v40, v40, v234
	v_sub_f32_e32 v41, v41, v234
	v_mfma_f32_32x32x16_bf16 v[96:111], a[144:147], v[208:211], v[96:111]
	v_sub_f32_e32 v42, v42, v234
	v_sub_f32_e32 v43, v43, v234
	v_sub_f32_e32 v44, v44, v234
	v_sub_f32_e32 v45, v45, v234
	v_sub_f32_e32 v46, v46, v234
	v_sub_f32_e32 v47, v47, v234
	v_sub_f32_e32 v48, v48, v234
	v_sub_f32_e32 v49, v49, v234
	v_mfma_f32_32x32x16_bf16 v[96:111], a[148:151], v[212:215], v[96:111]
	v_sub_f32_e32 v50, v50, v234
	v_sub_f32_e32 v51, v51, v234
	v_sub_f32_e32 v52, v52, v234
	v_sub_f32_e32 v53, v53, v234
	v_sub_f32_e32 v54, v54, v234
	v_sub_f32_e32 v55, v55, v234
	v_sub_f32_e32 v56, v56, v234
	v_sub_f32_e32 v57, v57, v234
	v_mfma_f32_32x32x16_bf16 v[112:127], a[152:155], v[208:211], v[112:127]
	v_sub_f32_e32 v58, v58, v234
	v_sub_f32_e32 v59, v59, v234
	v_sub_f32_e32 v60, v60, v234
	v_sub_f32_e32 v61, v61, v234
	v_sub_f32_e32 v62, v62, v234
	v_sub_f32_e32 v63, v63, v234
	v_exp_f32_e32 v32, v32
	v_exp_f32_e32 v33, v33
	v_mfma_f32_32x32x16_bf16 v[112:127], a[156:159], v[212:215], v[112:127]
	v_exp_f32_e32 v34, v34
	v_exp_f32_e32 v35, v35
	v_exp_f32_e32 v36, v36
	v_exp_f32_e32 v37, v37
	v_exp_f32_e32 v38, v38
	v_exp_f32_e32 v39, v39
	v_exp_f32_e32 v40, v40
	v_exp_f32_e32 v41, v41
	v_exp_f32_e32 v42, v42
	v_exp_f32_e32 v43, v43
	v_exp_f32_e32 v44, v44
	v_exp_f32_e32 v45, v45
	v_exp_f32_e32 v46, v46
	v_exp_f32_e32 v47, v47
	v_exp_f32_e32 v48, v48
	v_exp_f32_e32 v49, v49
	v_exp_f32_e32 v50, v50
	v_exp_f32_e32 v51, v51
	v_exp_f32_e32 v52, v52
	v_exp_f32_e32 v53, v53
	v_exp_f32_e32 v54, v54
	v_exp_f32_e32 v55, v55
	v_exp_f32_e32 v56, v56
	v_exp_f32_e32 v57, v57
	v_exp_f32_e32 v58, v58
	v_exp_f32_e32 v59, v59
	v_exp_f32_e32 v60, v60
	v_exp_f32_e32 v61, v61
	v_exp_f32_e32 v62, v62
	v_exp_f32_e32 v63, v63
	v_mul_f32_e32 v23, v23, v236
	v_add_f32_e32 v238, v32, v33
	v_add_f32_e32 v238, v238, v34
	v_add_f32_e32 v238, v238, v35
	v_add_f32_e32 v238, v238, v36
	v_add_f32_e32 v238, v238, v37
	v_add_f32_e32 v238, v238, v38
	v_add_f32_e32 v238, v238, v39
	v_add_f32_e32 v238, v238, v40
	v_add_f32_e32 v238, v238, v41
	v_add_f32_e32 v238, v238, v42
	v_add_f32_e32 v238, v238, v43
	v_add_f32_e32 v238, v238, v44
	v_add_f32_e32 v238, v238, v45
	v_add_f32_e32 v238, v238, v46
	v_add_f32_e32 v238, v238, v47
	v_add_f32_e32 v238, v238, v48
	v_add_f32_e32 v238, v238, v49
	v_add_f32_e32 v238, v238, v50
	v_add_f32_e32 v238, v238, v51
	v_add_f32_e32 v238, v238, v52
	v_add_f32_e32 v238, v238, v53
	v_add_f32_e32 v238, v238, v54
	v_add_f32_e32 v238, v238, v55
	v_add_f32_e32 v238, v238, v56
	v_add_f32_e32 v238, v238, v57
	v_add_f32_e32 v238, v238, v58
	v_add_f32_e32 v238, v238, v59
	v_add_f32_e32 v238, v238, v60
	v_add_f32_e32 v238, v238, v61
	v_add_f32_e32 v238, v238, v62
	v_add_f32_e32 v238, v238, v63
	v_add_f32_e32 v23, v23, v238
	v_pk_mul_f32 v[128:129], v[128:129], v[236:237] op_sel_hi:[1,0]
	v_pk_mul_f32 v[130:131], v[130:131], v[236:237] op_sel_hi:[1,0]
	v_pk_mul_f32 v[132:133], v[132:133], v[236:237] op_sel_hi:[1,0]
	v_pk_mul_f32 v[134:135], v[134:135], v[236:237] op_sel_hi:[1,0]
	v_pk_mul_f32 v[136:137], v[136:137], v[236:237] op_sel_hi:[1,0]
	v_pk_mul_f32 v[138:139], v[138:139], v[236:237] op_sel_hi:[1,0]
	v_pk_mul_f32 v[140:141], v[140:141], v[236:237] op_sel_hi:[1,0]
	v_pk_mul_f32 v[142:143], v[142:143], v[236:237] op_sel_hi:[1,0]
	v_pk_mul_f32 v[144:145], v[144:145], v[236:237] op_sel_hi:[1,0]
	v_pk_mul_f32 v[146:147], v[146:147], v[236:237] op_sel_hi:[1,0]
	v_pk_mul_f32 v[148:149], v[148:149], v[236:237] op_sel_hi:[1,0]
	v_pk_mul_f32 v[150:151], v[150:151], v[236:237] op_sel_hi:[1,0]
	v_pk_mul_f32 v[152:153], v[152:153], v[236:237] op_sel_hi:[1,0]
	v_pk_mul_f32 v[154:155], v[154:155], v[236:237] op_sel_hi:[1,0]
	v_pk_mul_f32 v[156:157], v[156:157], v[236:237] op_sel_hi:[1,0]
	v_pk_mul_f32 v[158:159], v[158:159], v[236:237] op_sel_hi:[1,0]
	v_pk_mul_f32 v[160:161], v[160:161], v[236:237] op_sel_hi:[1,0]
	v_pk_mul_f32 v[162:163], v[162:163], v[236:237] op_sel_hi:[1,0]
	v_pk_mul_f32 v[164:165], v[164:165], v[236:237] op_sel_hi:[1,0]
	v_pk_mul_f32 v[166:167], v[166:167], v[236:237] op_sel_hi:[1,0]
	v_pk_mul_f32 v[168:169], v[168:169], v[236:237] op_sel_hi:[1,0]
	v_pk_mul_f32 v[170:171], v[170:171], v[236:237] op_sel_hi:[1,0]
	v_pk_mul_f32 v[172:173], v[172:173], v[236:237] op_sel_hi:[1,0]
	v_pk_mul_f32 v[174:175], v[174:175], v[236:237] op_sel_hi:[1,0]
	v_pk_mul_f32 v[176:177], v[176:177], v[236:237] op_sel_hi:[1,0]
	v_pk_mul_f32 v[178:179], v[178:179], v[236:237] op_sel_hi:[1,0]
	v_pk_mul_f32 v[180:181], v[180:181], v[236:237] op_sel_hi:[1,0]
	v_pk_mul_f32 v[182:183], v[182:183], v[236:237] op_sel_hi:[1,0]
	v_pk_mul_f32 v[184:185], v[184:185], v[236:237] op_sel_hi:[1,0]
	v_pk_mul_f32 v[186:187], v[186:187], v[236:237] op_sel_hi:[1,0]
	v_pk_mul_f32 v[188:189], v[188:189], v[236:237] op_sel_hi:[1,0]
	v_pk_mul_f32 v[190:191], v[190:191], v[236:237] op_sel_hi:[1,0]
	v_cvt_pk_bf16_f32 v32, v32, v33
	v_cvt_pk_bf16_f32 v33, v34, v35
	v_cvt_pk_bf16_f32 v34, v36, v37
	v_cvt_pk_bf16_f32 v35, v38, v39
	v_cvt_pk_bf16_f32 v36, v40, v41
	v_cvt_pk_bf16_f32 v37, v42, v43
	v_cvt_pk_bf16_f32 v38, v44, v45
	v_cvt_pk_bf16_f32 v39, v46, v47
	v_cvt_pk_bf16_f32 v48, v48, v49
	v_cvt_pk_bf16_f32 v49, v50, v51
	v_cvt_pk_bf16_f32 v50, v52, v53
	v_cvt_pk_bf16_f32 v51, v54, v55
	v_cvt_pk_bf16_f32 v52, v56, v57
	v_cvt_pk_bf16_f32 v53, v58, v59
	v_cvt_pk_bf16_f32 v54, v60, v61
	v_cvt_pk_bf16_f32 v55, v62, v63
	s_nop 1
	v_mfma_f32_32x32x16_bf16 v[128:143], a[96:99], v[32:35], v[128:143]
	v_mfma_f32_32x32x16_bf16 v[128:143], a[100:103], v[36:39], v[128:143]
	v_mfma_f32_32x32x16_bf16 v[144:159], a[104:107], v[32:35], v[144:159]
	v_mfma_f32_32x32x16_bf16 v[144:159], a[108:111], v[36:39], v[144:159]
	v_mfma_f32_32x32x16_bf16 v[160:175], a[112:115], v[32:35], v[160:175]
	v_mfma_f32_32x32x16_bf16 v[160:175], a[116:119], v[36:39], v[160:175]
	v_mfma_f32_32x32x16_bf16 v[176:191], a[120:123], v[32:35], v[176:191]
	v_mfma_f32_32x32x16_bf16 v[176:191], a[124:127], v[36:39], v[176:191]
	v_mfma_f32_32x32x16_bf16 v[128:143], a[128:131], v[48:51], v[128:143]
	v_mfma_f32_32x32x16_bf16 v[128:143], a[132:135], v[52:55], v[128:143]
	v_mfma_f32_32x32x16_bf16 v[144:159], a[136:139], v[48:51], v[144:159]
	v_mfma_f32_32x32x16_bf16 v[144:159], a[140:143], v[52:55], v[144:159]
	v_mfma_f32_32x32x16_bf16 v[160:175], a[144:147], v[48:51], v[160:175]
	v_mfma_f32_32x32x16_bf16 v[160:175], a[148:151], v[52:55], v[160:175]
	v_mfma_f32_32x32x16_bf16 v[176:191], a[152:155], v[48:51], v[176:191]
	v_mfma_f32_32x32x16_bf16 v[176:191], a[156:159], v[52:55], v[176:191]
.Lat_skip:
	s_xor_b32 s87, s87, 0x8c00
	v_add_u32_e32 v17, s87, v16
	v_add_u32_e32 v19, s87, v18
	s_waitcnt vmcnt(0)
	ds_write_b128 v17, a[224:227] offset:0
	ds_write_b128 v17, a[228:231] offset:4352
	ds_write_b128 v17, a[232:235] offset:8704
	ds_write_b128 v17, a[236:239] offset:13056
	ds_write_b128 v19, a[240:243] offset:0
	ds_write_b128 v19, a[244:247] offset:4608
	ds_write_b128 v19, a[248:251] offset:9216
	ds_write_b128 v19, a[252:255] offset:13824
	s_waitcnt lgkmcnt(0)
	s_barrier
	s_add_u32 s86, s86, 1
	s_add_u32 s85, s85, 64
	v_subrev_u32_e32 v25, 64, v25
	s_cmp_lt_u32 s86, s17
	s_cbranch_scc1 .Lat_kb
	s_nop 15
	ds_bpermute_b32 v232, v26, v22
	ds_bpermute_b32 v233, v26, v23
	s_waitcnt lgkmcnt(0)
	v_add_f32_e32 v232, v232, v22
	v_add_f32_e32 v233, v233, v23
	v_rcp_f32_e32 v232, v232
	v_rcp_f32_e32 v233, v233
	s_nop 0
	v_mul_f32_e32 v233, v24, v233
	v_mul_f32_e32 v128, v128, v233
	v_mul_f32_e32 v129, v129, v233
	v_mul_f32_e32 v130, v130, v233
	v_mul_f32_e32 v131, v131, v233
	v_mul_f32_e32 v132, v132, v233
	v_mul_f32_e32 v133, v133, v233
	v_mul_f32_e32 v134, v134, v233
	v_mul_f32_e32 v135, v135, v233
	v_mul_f32_e32 v136, v136, v233
	v_mul_f32_e32 v137, v137, v233
	v_mul_f32_e32 v138, v138, v233
	v_mul_f32_e32 v139, v139, v233
	v_mul_f32_e32 v140, v140, v233
	v_mul_f32_e32 v141, v141, v233
	v_mul_f32_e32 v142, v142, v233
	v_mul_f32_e32 v143, v143, v233
	v_mul_f32_e32 v144, v144, v233
	v_mul_f32_e32 v145, v145, v233
	v_mul_f32_e32 v146, v146, v233
	v_mul_f32_e32 v147, v147, v233
	v_mul_f32_e32 v148, v148, v233
	v_mul_f32_e32 v149, v149, v233
	v_mul_f32_e32 v150, v150, v233
	v_mul_f32_e32 v151, v151, v233
	v_mul_f32_e32 v152, v152, v233
	v_mul_f32_e32 v153, v153, v233
	v_mul_f32_e32 v154, v154, v233
	v_mul_f32_e32 v155, v155, v233
	v_mul_f32_e32 v156, v156, v233
	v_mul_f32_e32 v157, v157, v233
	v_mul_f32_e32 v158, v158, v233
	v_mul_f32_e32 v159, v159, v233
	v_mul_f32_e32 v160, v160, v233
	v_mul_f32_e32 v161, v161, v233
	v_mul_f32_e32 v162, v162, v233
	v_mul_f32_e32 v163, v163, v233
	v_mul_f32_e32 v164, v164, v233
	v_mul_f32_e32 v165, v165, v233
	v_mul_f32_e32 v166, v166, v233
	v_mul_f32_e32 v167, v167, v233
	v_mul_f32_e32 v168, v168, v233
	v_mul_f32_e32 v169, v169, v233
	v_mul_f32_e32 v170, v170, v233
	v_mul_f32_e32 v171, v171, v233
	v_mul_f32_e32 v172, v172, v233
	v_mul_f32_e32 v173, v173, v233
	v_mul_f32_e32 v174, v174, v233
	v_mul_f32_e32 v175, v175, v233
	v_mul_f32_e32 v176, v176, v233
	v_mul_f32_e32 v177, v177, v233
	v_mul_f32_e32 v178, v178, v233
	v_mul_f32_e32 v179, v179, v233
	v_mul_f32_e32 v180, v180, v233
	v_mul_f32_e32 v181, v181, v233
	v_mul_f32_e32 v182, v182, v233
	v_mul_f32_e32 v183, v183, v233
	v_mul_f32_e32 v184, v184, v233
	v_mul_f32_e32 v185, v185, v233
	v_mul_f32_e32 v186, v186, v233
	v_mul_f32_e32 v187, v187, v233
	v_mul_f32_e32 v188, v188, v233
	v_mul_f32_e32 v189, v189, v233
	v_mul_f32_e32 v190, v190, v233
	v_mul_f32_e32 v191, v191, v233
	v_fma_f32 v64, v64, v232, -v128
	v_fma_f32 v65, v65, v232, -v129
	v_fma_f32 v66, v66, v232, -v130
	v_fma_f32 v67, v67, v232, -v131
	v_fma_f32 v68, v68, v232, -v132
	v_fma_f32 v69, v69, v232, -v133
	v_fma_f32 v70, v70, v232, -v134
	v_fma_f32 v71, v71, v232, -v135
	v_fma_f32 v72, v72, v232, -v136
	v_fma_f32 v73, v73, v232, -v137
	v_fma_f32 v74, v74, v232, -v138
	v_fma_f32 v75, v75, v232, -v139
	v_fma_f32 v76, v76, v232, -v140
	v_fma_f32 v77, v77, v232, -v141
	v_fma_f32 v78, v78, v232, -v142
	v_fma_f32 v79, v79, v232, -v143
	v_fma_f32 v80, v80, v232, -v144
	v_fma_f32 v81, v81, v232, -v145
	v_fma_f32 v82, v82, v232, -v146
	v_fma_f32 v83, v83, v232, -v147
	v_fma_f32 v84, v84, v232, -v148
	v_fma_f32 v85, v85, v232, -v149
	v_fma_f32 v86, v86, v232, -v150
	v_fma_f32 v87, v87, v232, -v151
	v_fma_f32 v88, v88, v232, -v152
	v_fma_f32 v89, v89, v232, -v153
	v_fma_f32 v90, v90, v232, -v154
	v_fma_f32 v91, v91, v232, -v155
	v_fma_f32 v92, v92, v232, -v156
	v_fma_f32 v93, v93, v232, -v157
	v_fma_f32 v94, v94, v232, -v158
	v_fma_f32 v95, v95, v232, -v159
	v_fma_f32 v96, v96, v232, -v160
	v_fma_f32 v97, v97, v232, -v161
	v_fma_f32 v98, v98, v232, -v162
	v_fma_f32 v99, v99, v232, -v163
	v_fma_f32 v100, v100, v232, -v164
	v_fma_f32 v101, v101, v232, -v165
	v_fma_f32 v102, v102, v232, -v166
	v_fma_f32 v103, v103, v232, -v167
	v_fma_f32 v104, v104, v232, -v168
	v_fma_f32 v105, v105, v232, -v169
	v_fma_f32 v106, v106, v232, -v170
	v_fma_f32 v107, v107, v232, -v171
	v_fma_f32 v108, v108, v232, -v172
	v_fma_f32 v109, v109, v232, -v173
	v_fma_f32 v110, v110, v232, -v174
	v_fma_f32 v111, v111, v232, -v175
	v_fma_f32 v112, v112, v232, -v176
	v_fma_f32 v113, v113, v232, -v177
	v_fma_f32 v114, v114, v232, -v178
	v_fma_f32 v115, v115, v232, -v179
	v_fma_f32 v116, v116, v232, -v180
	v_fma_f32 v117, v117, v232, -v181
	v_fma_f32 v118, v118, v232, -v182
	v_fma_f32 v119, v119, v232, -v183
	v_fma_f32 v120, v120, v232, -v184
	v_fma_f32 v121, v121, v232, -v185
	v_fma_f32 v122, v122, v232, -v186
	v_fma_f32 v123, v123, v232, -v187
	v_fma_f32 v124, v124, v232, -v188
	v_fma_f32 v125, v125, v232, -v189
	v_fma_f32 v126, v126, v232, -v190
	v_fma_f32 v127, v127, v232, -v191
	v_mul_f32_e32 v234, v64, v64
	v_fmac_f32_e32 v234, v65, v65
	v_fmac_f32_e32 v234, v66, v66
	v_fmac_f32_e32 v234, v67, v67
	v_fmac_f32_e32 v234, v68, v68
	v_fmac_f32_e32 v234, v69, v69
	v_fmac_f32_e32 v234, v70, v70
	v_fmac_f32_e32 v234, v71, v71
	v_fmac_f32_e32 v234, v72, v72
	v_fmac_f32_e32 v234, v73, v73
	v_fmac_f32_e32 v234, v74, v74
	v_fmac_f32_e32 v234, v75, v75
	v_fmac_f32_e32 v234, v76, v76
	v_fmac_f32_e32 v234, v77, v77
	v_fmac_f32_e32 v234, v78, v78
	v_fmac_f32_e32 v234, v79, v79
	v_fmac_f32_e32 v234, v80, v80
	v_fmac_f32_e32 v234, v81, v81
	v_fmac_f32_e32 v234, v82, v82
	v_fmac_f32_e32 v234, v83, v83
	v_fmac_f32_e32 v234, v84, v84
	v_fmac_f32_e32 v234, v85, v85
	v_fmac_f32_e32 v234, v86, v86
	v_fmac_f32_e32 v234, v87, v87
	v_fmac_f32_e32 v234, v88, v88
	v_fmac_f32_e32 v234, v89, v89
	v_fmac_f32_e32 v234, v90, v90
	v_fmac_f32_e32 v234, v91, v91
	v_fmac_f32_e32 v234, v92, v92
	v_fmac_f32_e32 v234, v93, v93
	v_fmac_f32_e32 v234, v94, v94
	v_fmac_f32_e32 v234, v95, v95
	v_fmac_f32_e32 v234, v96, v96
	v_fmac_f32_e32 v234, v97, v97
	v_fmac_f32_e32 v234, v98, v98
	v_fmac_f32_e32 v234, v99, v99
	v_fmac_f32_e32 v234, v100, v100
	v_fmac_f32_e32 v234, v101, v101
	v_fmac_f32_e32 v234, v102, v102
	v_fmac_f32_e32 v234, v103, v103
	v_fmac_f32_e32 v234, v104, v104
	v_fmac_f32_e32 v234, v105, v105
	v_fmac_f32_e32 v234, v106, v106
	v_fmac_f32_e32 v234, v107, v107
	v_fmac_f32_e32 v234, v108, v108
	v_fmac_f32_e32 v234, v109, v109
	v_fmac_f32_e32 v234, v110, v110
	v_fmac_f32_e32 v234, v111, v111
	v_fmac_f32_e32 v234, v112, v112
	v_fmac_f32_e32 v234, v113, v113
	v_fmac_f32_e32 v234, v114, v114
	v_fmac_f32_e32 v234, v115, v115
	v_fmac_f32_e32 v234, v116, v116
	v_fmac_f32_e32 v234, v117, v117
	v_fmac_f32_e32 v234, v118, v118
	v_fmac_f32_e32 v234, v119, v119
	v_fmac_f32_e32 v234, v120, v120
	v_fmac_f32_e32 v234, v121, v121
	v_fmac_f32_e32 v234, v122, v122
	v_fmac_f32_e32 v234, v123, v123
	v_fmac_f32_e32 v234, v124, v124
	v_fmac_f32_e32 v234, v125, v125
	v_fmac_f32_e32 v234, v126, v126
	v_fmac_f32_e32 v234, v127, v127
	ds_bpermute_b32 v235, v26, v234
	s_waitcnt lgkmcnt(0)
	v_add_f32_e32 v234, v234, v235
	v_mov_b32_e32 v235, 0x3727c5ac
	v_fmamk_f32 v234, v234, 0x3c000000, v235
	v_rsq_f32_e32 v234, v234
	s_nop 0
	v_mul_f32_e32 v234, s12, v234
	s_lshl_b32 s20, s19, 11
	s_lshl_b32 s21, s14, 8
	s_add_u32 s20, s20, s21
	s_add_u32 s76, s92, 0x22100000
	s_addc_u32 s77, s93, 0
	s_add_u32 s76, s76, s20
	s_addc_u32 s77, s77, 0
	v_lshlrev_b32_e32 v28, 11, v30
	v_lshl_add_u32 v28, v2, 3, v28
	v_accvgpr_read_b32 v236, a160
	v_accvgpr_read_b32 v237, a161
	v_accvgpr_read_b32 v238, a162
	v_accvgpr_read_b32 v239, a163
	v_mul_f32_e32 v64, v64, v234
	v_mul_f32_e32 v65, v65, v234
	v_mul_f32_e32 v66, v66, v234
	v_mul_f32_e32 v67, v67, v234
	v_mul_f32_e32 v64, v64, v236
	v_mul_f32_e32 v65, v65, v237
	v_mul_f32_e32 v66, v66, v238
	v_mul_f32_e32 v67, v67, v239
	v_cvt_pk_bf16_f32 v240, v64, v65
	v_cvt_pk_bf16_f32 v241, v66, v67
	global_store_dwordx2 v28, v[240:241], s[76:77] offset:0
	v_accvgpr_read_b32 v236, a164
	v_accvgpr_read_b32 v237, a165
	v_accvgpr_read_b32 v238, a166
	v_accvgpr_read_b32 v239, a167
	v_mul_f32_e32 v68, v68, v234
	v_mul_f32_e32 v69, v69, v234
	v_mul_f32_e32 v70, v70, v234
	v_mul_f32_e32 v71, v71, v234
	v_mul_f32_e32 v68, v68, v236
	v_mul_f32_e32 v69, v69, v237
	v_mul_f32_e32 v70, v70, v238
	v_mul_f32_e32 v71, v71, v239
	v_cvt_pk_bf16_f32 v240, v68, v69
	v_cvt_pk_bf16_f32 v241, v70, v71
	global_store_dwordx2 v28, v[240:241], s[76:77] offset:16
	v_accvgpr_read_b32 v236, a168
	v_accvgpr_read_b32 v237, a169
	v_accvgpr_read_b32 v238, a170
	v_accvgpr_read_b32 v239, a171
	v_mul_f32_e32 v72, v72, v234
	v_mul_f32_e32 v73, v73, v234
	v_mul_f32_e32 v74, v74, v234
	v_mul_f32_e32 v75, v75, v234
	v_mul_f32_e32 v72, v72, v236
	v_mul_f32_e32 v73, v73, v237
	v_mul_f32_e32 v74, v74, v238
	v_mul_f32_e32 v75, v75, v239
	v_cvt_pk_bf16_f32 v240, v72, v73
	v_cvt_pk_bf16_f32 v241, v74, v75
	global_store_dwordx2 v28, v[240:241], s[76:77] offset:32
	v_accvgpr_read_b32 v236, a172
	v_accvgpr_read_b32 v237, a173
	v_accvgpr_read_b32 v238, a174
	v_accvgpr_read_b32 v239, a175
	v_mul_f32_e32 v76, v76, v234
	v_mul_f32_e32 v77, v77, v234
	v_mul_f32_e32 v78, v78, v234
	v_mul_f32_e32 v79, v79, v234
	v_mul_f32_e32 v76, v76, v236
	v_mul_f32_e32 v77, v77, v237
	v_mul_f32_e32 v78, v78, v238
	v_mul_f32_e32 v79, v79, v239
	v_cvt_pk_bf16_f32 v240, v76, v77
	v_cvt_pk_bf16_f32 v241, v78, v79
	global_store_dwordx2 v28, v[240:241], s[76:77] offset:48
	v_accvgpr_read_b32 v236, a176
	v_accvgpr_read_b32 v237, a177
	v_accvgpr_read_b32 v238, a178
	v_accvgpr_read_b32 v239, a179
	v_mul_f32_e32 v80, v80, v234
	v_mul_f32_e32 v81, v81, v234
	v_mul_f32_e32 v82, v82, v234
	v_mul_f32_e32 v83, v83, v234
	v_mul_f32_e32 v80, v80, v236
	v_mul_f32_e32 v81, v81, v237
	v_mul_f32_e32 v82, v82, v238
	v_mul_f32_e32 v83, v83, v239
	v_cvt_pk_bf16_f32 v240, v80, v81
	v_cvt_pk_bf16_f32 v241, v82, v83
	global_store_dwordx2 v28, v[240:241], s[76:77] offset:64
	v_accvgpr_read_b32 v236, a180
	v_accvgpr_read_b32 v237, a181
	v_accvgpr_read_b32 v238, a182
	v_accvgpr_read_b32 v239, a183
	v_mul_f32_e32 v84, v84, v234
	v_mul_f32_e32 v85, v85, v234
	v_mul_f32_e32 v86, v86, v234
	v_mul_f32_e32 v87, v87, v234
	v_mul_f32_e32 v84, v84, v236
	v_mul_f32_e32 v85, v85, v237
	v_mul_f32_e32 v86, v86, v238
	v_mul_f32_e32 v87, v87, v239
	v_cvt_pk_bf16_f32 v240, v84, v85
	v_cvt_pk_bf16_f32 v241, v86, v87
	global_store_dwordx2 v28, v[240:241], s[76:77] offset:80
	v_accvgpr_read_b32 v236, a184
	v_accvgpr_read_b32 v237, a185
	v_accvgpr_read_b32 v238, a186
	v_accvgpr_read_b32 v239, a187
	v_mul_f32_e32 v88, v88, v234
	v_mul_f32_e32 v89, v89, v234
	v_mul_f32_e32 v90, v90, v234
	v_mul_f32_e32 v91, v91, v234
	v_mul_f32_e32 v88, v88, v236
	v_mul_f32_e32 v89, v89, v237
	v_mul_f32_e32 v90, v90, v238
	v_mul_f32_e32 v91, v91, v239
	v_cvt_pk_bf16_f32 v240, v88, v89
	v_cvt_pk_bf16_f32 v241, v90, v91
	global_store_dwordx2 v28, v[240:241], s[76:77] offset:96
	v_accvgpr_read_b32 v236, a188
	v_accvgpr_read_b32 v237, a189
	v_accvgpr_read_b32 v238, a190
	v_accvgpr_read_b32 v239, a191
	v_mul_f32_e32 v92, v92, v234
	v_mul_f32_e32 v93, v93, v234
	v_mul_f32_e32 v94, v94, v234
	v_mul_f32_e32 v95, v95, v234
	v_mul_f32_e32 v92, v92, v236
	v_mul_f32_e32 v93, v93, v237
	v_mul_f32_e32 v94, v94, v238
	v_mul_f32_e32 v95, v95, v239
	v_cvt_pk_bf16_f32 v240, v92, v93
	v_cvt_pk_bf16_f32 v241, v94, v95
	global_store_dwordx2 v28, v[240:241], s[76:77] offset:112
	v_accvgpr_read_b32 v236, a192
	v_accvgpr_read_b32 v237, a193
	v_accvgpr_read_b32 v238, a194
	v_accvgpr_read_b32 v239, a195
	v_mul_f32_e32 v96, v96, v234
	v_mul_f32_e32 v97, v97, v234
	v_mul_f32_e32 v98, v98, v234
	v_mul_f32_e32 v99, v99, v234
	v_mul_f32_e32 v96, v96, v236
	v_mul_f32_e32 v97, v97, v237
	v_mul_f32_e32 v98, v98, v238
	v_mul_f32_e32 v99, v99, v239
	v_cvt_pk_bf16_f32 v240, v96, v97
	v_cvt_pk_bf16_f32 v241, v98, v99
	global_store_dwordx2 v28, v[240:241], s[76:77] offset:128
	v_accvgpr_read_b32 v236, a196
	v_accvgpr_read_b32 v237, a197
	v_accvgpr_read_b32 v238, a198
	v_accvgpr_read_b32 v239, a199
	v_mul_f32_e32 v100, v100, v234
	v_mul_f32_e32 v101, v101, v234
	v_mul_f32_e32 v102, v102, v234
	v_mul_f32_e32 v103, v103, v234
	v_mul_f32_e32 v100, v100, v236
	v_mul_f32_e32 v101, v101, v237
	v_mul_f32_e32 v102, v102, v238
	v_mul_f32_e32 v103, v103, v239
	v_cvt_pk_bf16_f32 v240, v100, v101
	v_cvt_pk_bf16_f32 v241, v102, v103
	global_store_dwordx2 v28, v[240:241], s[76:77] offset:144
	v_accvgpr_read_b32 v236, a200
	v_accvgpr_read_b32 v237, a201
	v_accvgpr_read_b32 v238, a202
	v_accvgpr_read_b32 v239, a203
	v_mul_f32_e32 v104, v104, v234
	v_mul_f32_e32 v105, v105, v234
	v_mul_f32_e32 v106, v106, v234
	v_mul_f32_e32 v107, v107, v234
	v_mul_f32_e32 v104, v104, v236
	v_mul_f32_e32 v105, v105, v237
	v_mul_f32_e32 v106, v106, v238
	v_mul_f32_e32 v107, v107, v239
	v_cvt_pk_bf16_f32 v240, v104, v105
	v_cvt_pk_bf16_f32 v241, v106, v107
	global_store_dwordx2 v28, v[240:241], s[76:77] offset:160
	v_accvgpr_read_b32 v236, a204
	v_accvgpr_read_b32 v237, a205
	v_accvgpr_read_b32 v238, a206
	v_accvgpr_read_b32 v239, a207
	v_mul_f32_e32 v108, v108, v234
	v_mul_f32_e32 v109, v109, v234
	v_mul_f32_e32 v110, v110, v234
	v_mul_f32_e32 v111, v111, v234
	v_mul_f32_e32 v108, v108, v236
	v_mul_f32_e32 v109, v109, v237
	v_mul_f32_e32 v110, v110, v238
	v_mul_f32_e32 v111, v111, v239
	v_cvt_pk_bf16_f32 v240, v108, v109
	v_cvt_pk_bf16_f32 v241, v110, v111
	global_store_dwordx2 v28, v[240:241], s[76:77] offset:176
	v_accvgpr_read_b32 v236, a208
	v_accvgpr_read_b32 v237, a209
	v_accvgpr_read_b32 v238, a210
	v_accvgpr_read_b32 v239, a211
	v_mul_f32_e32 v112, v112, v234
	v_mul_f32_e32 v113, v113, v234
	v_mul_f32_e32 v114, v114, v234
	v_mul_f32_e32 v115, v115, v234
	v_mul_f32_e32 v112, v112, v236
	v_mul_f32_e32 v113, v113, v237
	v_mul_f32_e32 v114, v114, v238
	v_mul_f32_e32 v115, v115, v239
	v_cvt_pk_bf16_f32 v240, v112, v113
	v_cvt_pk_bf16_f32 v241, v114, v115
	global_store_dwordx2 v28, v[240:241], s[76:77] offset:192
	v_accvgpr_read_b32 v236, a212
	v_accvgpr_read_b32 v237, a213
	v_accvgpr_read_b32 v238, a214
	v_accvgpr_read_b32 v239, a215
	v_mul_f32_e32 v116, v116, v234
	v_mul_f32_e32 v117, v117, v234
	v_mul_f32_e32 v118, v118, v234
	v_mul_f32_e32 v119, v119, v234
	v_mul_f32_e32 v116, v116, v236
	v_mul_f32_e32 v117, v117, v237
	v_mul_f32_e32 v118, v118, v238
	v_mul_f32_e32 v119, v119, v239
	v_cvt_pk_bf16_f32 v240, v116, v117
	v_cvt_pk_bf16_f32 v241, v118, v119
	global_store_dwordx2 v28, v[240:241], s[76:77] offset:208
	v_accvgpr_read_b32 v236, a216
	v_accvgpr_read_b32 v237, a217
	v_accvgpr_read_b32 v238, a218
	v_accvgpr_read_b32 v239, a219
	v_mul_f32_e32 v120, v120, v234
	v_mul_f32_e32 v121, v121, v234
	v_mul_f32_e32 v122, v122, v234
	v_mul_f32_e32 v123, v123, v234
	v_mul_f32_e32 v120, v120, v236
	v_mul_f32_e32 v121, v121, v237
	v_mul_f32_e32 v122, v122, v238
	v_mul_f32_e32 v123, v123, v239
	v_cvt_pk_bf16_f32 v240, v120, v121
	v_cvt_pk_bf16_f32 v241, v122, v123
	global_store_dwordx2 v28, v[240:241], s[76:77] offset:224
	v_accvgpr_read_b32 v236, a220
	v_accvgpr_read_b32 v237, a221
	v_accvgpr_read_b32 v238, a222
	v_accvgpr_read_b32 v239, a223
	v_mul_f32_e32 v124, v124, v234
	v_mul_f32_e32 v125, v125, v234
	v_mul_f32_e32 v126, v126, v234
	v_mul_f32_e32 v127, v127, v234
	v_mul_f32_e32 v124, v124, v236
	v_mul_f32_e32 v125, v125, v237
	v_mul_f32_e32 v126, v126, v238
	v_mul_f32_e32 v127, v127, v239
	v_cvt_pk_bf16_f32 v240, v124, v125
	v_cvt_pk_bf16_f32 v241, v126, v127
	global_store_dwordx2 v28, v[240:241], s[76:77] offset:240
	s_add_u32 s22, s22, s8
	s_cmp_lt_u32 s22, 0x800
	s_cbranch_scc1 .Lat_item
